# softmax row-sum in the three attention loops: 33-long dependent v_add_f32 chain split into two independent f32 chains (summation order only)
# baseline (speedup 1.0000x reference)
; __device__ __forceinline__ void finishSM(f32x16& p0, f32x16& p1, float alpha, float& l_reg, bf16x8& pa0, bf16x8& pa1, bf16x8& pa2, bf16x8& pa3) {
; #pragma unroll
;   for (int r = 0; r < 16; ++r) p1[r] = __builtin_amdgcn_exp2f(p1[r]);
;   float ps = 0;
; #pragma unroll
;   for (int r = 0; r < 16; ++r) ps += p0[r];
; #pragma unroll
;   for (int r = 0; r < 16; ++r) ps += p1[r];
;   { auto rr = __builtin_amdgcn_permlane32_swap(__float_as_uint(ps), __float_as_uint(ps), false, false);
;     ps = __uint_as_float(rr[0]) + __uint_as_float(rr[1]); }
;   l_reg = l_reg * alpha + ps;
;     ...
;   PK4(p0, 0, pa0); PK4(p0, 8, pa1); PK4(p1, 0, pa2); PK4(p1, 8, pa3);
;     ...
; }
; template <int DQK, int KW, int QSP> __device__ __forceinline__ void qkt(f32x16& p0, f32x16& p1, const char* Ks, const int (&kb)[4], const bf16x8* qr, const char* qsp, const f32x16& cinit) {
;   p0 = cinit; p1 = cinit;
;   constexpr int N = DQK / 16;
;     ...
;   bf16x8 f0[2], f1[2];
;   f0[0] = KRD(0, 1); f1[0] = KRD(0, 0);
; #pragma unroll
;   for (int d0 = 0; d0 < N; ++d0) {
;     if (d0 + 1 < N) { f0[(d0 + 1) & 1] = KRD(d0 + 1, 1); f1[(d0 + 1) & 1] = KRD(d0 + 1, 0); }
;     __builtin_amdgcn_sched_barrier(0x406);
;     bf16x8 qf;
;     if constexpr (QSP > 0) { if (d0 >= N - QSP) qf = *reinterpret_cast<const bf16x8*>(qsp + (d0 - (N - QSP)) * 1024); else qf = qr[d0]; } else qf = qr[d0];
;     p0 = __builtin_amdgcn_mfma_f32_32x32x16_bf16(f0[d0 & 1], qf, p0, 0, 0, 0);
;     p1 = __builtin_amdgcn_mfma_f32_32x32x16_bf16(f1[d0 & 1], qf, p1, 0, 0, 0);
;     __builtin_amdgcn_sched_barrier(0x406); }
;     ...
; }
.LBB0_51:
	s_mul_i32 s6, s8, 0x6000
	s_add_i32 s6, s6, 0
	v_add_u32_e32 v210, s6, v207
	v_add_u32_e32 v211, s6, v200
	ds_read_b128 v[154:157], v210 offset:49152
	ds_read_b128 v[158:161], v210 offset:61440
	ds_read_b128 v[66:69], v211 offset:61440
	ds_read_b128 v[70:73], v211 offset:49152
	v_add_u32_e32 v223, s6, v205
	v_add_u32_e32 v229, s6, v206
	s_waitcnt lgkmcnt(0)
	v_mfma_f32_32x32x16_bf16 v[82:97], v[70:73], v[130:133], 0
	v_exp_f32_e32 v182, v182
	v_exp_f32_e32 v183, v183
	v_exp_f32_e32 v180, v180
	v_exp_f32_e32 v181, v181
	v_exp_f32_e32 v178, v178
	v_exp_f32_e32 v179, v179
	v_exp_f32_e32 v176, v176
	v_mfma_f32_32x32x16_bf16 v[66:81], v[66:69], v[130:133], 0
	ds_read_b128 v[230:233], v223 offset:49152
	ds_read_b128 v[234:237], v223 offset:61440
	v_exp_f32_e32 v177, v177
	v_exp_f32_e32 v168, v168
	v_exp_f32_e32 v169, v169
	v_exp_f32_e32 v167, v167
	v_mfma_f32_32x32x16_bf16 v[66:81], v[158:161], v[126:129], v[66:81]
	v_mfma_f32_32x32x16_bf16 v[82:97], v[154:157], v[126:129], v[82:97]
	ds_read_b128 v[154:157], v229 offset:49152
	ds_read_b128 v[158:161], v229 offset:61440
	s_waitcnt lgkmcnt(2)
	v_mfma_f32_32x32x16_bf16 v[66:81], v[234:237], v[122:125], v[66:81]
	v_mfma_f32_32x32x16_bf16 v[82:97], v[230:233], v[122:125], v[82:97]
	ds_read_b128 v[230:233], v211 offset:49280
	ds_read_b128 v[234:237], v211 offset:61568
	s_waitcnt lgkmcnt(2)
	v_mfma_f32_32x32x16_bf16 v[66:81], v[158:161], v[118:121], v[66:81]
	v_mfma_f32_32x32x16_bf16 v[82:97], v[154:157], v[118:121], v[82:97]
	ds_read_b128 v[154:157], v210 offset:49280
	ds_read_b128 v[158:161], v210 offset:61568
	s_waitcnt lgkmcnt(2)
	v_mfma_f32_32x32x16_bf16 v[66:81], v[234:237], v[114:117], v[66:81]
	v_mfma_f32_32x32x16_bf16 v[82:97], v[230:233], v[114:117], v[82:97]
	ds_read_b128 v[230:233], v223 offset:49280
	ds_read_b128 v[234:237], v223 offset:61568
	s_waitcnt lgkmcnt(2)
	v_mfma_f32_32x32x16_bf16 v[66:81], v[158:161], v[110:113], v[66:81]
	v_mfma_f32_32x32x16_bf16 v[82:97], v[154:157], v[110:113], v[82:97]
	ds_read_b128 v[154:157], v229 offset:49280
	ds_read_b128 v[158:161], v229 offset:61568
	s_waitcnt lgkmcnt(2)
	v_mfma_f32_32x32x16_bf16 v[66:81], v[234:237], v[106:109], v[66:81]
	v_mfma_f32_32x32x16_bf16 v[82:97], v[230:233], v[106:109], v[82:97]
	ds_read_b128 v[230:233], v211 offset:49408
	ds_read_b128 v[234:237], v211 offset:61696
	s_waitcnt lgkmcnt(2)
	v_mfma_f32_32x32x16_bf16 v[66:81], v[158:161], v[102:105], v[66:81]
	v_mfma_f32_32x32x16_bf16 v[82:97], v[154:157], v[102:105], v[82:97]
	ds_read_b128 v[154:157], v210 offset:49408
	ds_read_b128 v[158:161], v210 offset:61696
	s_waitcnt lgkmcnt(2)
	v_mfma_f32_32x32x16_bf16 v[66:81], v[234:237], v[98:101], v[66:81]
	v_mfma_f32_32x32x16_bf16 v[82:97], v[230:233], v[98:101], v[82:97]
	ds_read_b128 v[230:233], v223 offset:49408
	ds_read_b128 v[234:237], v223 offset:61696
	v_exp_f32_e32 v223, v166
	s_waitcnt lgkmcnt(2)
	v_mfma_f32_32x32x16_bf16 v[66:81], v[158:161], v[248:251], v[66:81]
	v_mfma_f32_32x32x16_bf16 v[82:97], v[154:157], v[248:251], v[82:97]
	ds_read_b128 v[158:161], v229 offset:49408
	ds_read_b128 v[154:157], v229 offset:61696
	ds_read_b128 v[238:241], v197 offset:1024
	v_exp_f32_e32 v229, v164
	s_waitcnt lgkmcnt(0)
	v_mfma_f32_32x32x16_bf16 v[66:81], v[234:237], v[238:241], v[66:81]
	v_mfma_f32_32x32x16_bf16 v[82:97], v[230:233], v[238:241], v[82:97]
	ds_read_b128 v[230:233], v197 offset:2048
	s_waitcnt lgkmcnt(0)
	v_mfma_f32_32x32x16_bf16 v[66:81], v[154:157], v[230:233], v[66:81]
	v_add_f32_e32 v154, 0, v226
	v_add_f32_e32 v252, 0, v228
	v_add_f32_e32 v154, v224, v154
	v_add_f32_e32 v252, v227, v252
	v_add_f32_e32 v154, v221, v154
	v_add_f32_e32 v252, v225, v252
	v_add_f32_e32 v154, v220, v154
	v_add_f32_e32 v252, v222, v252
	v_add_f32_e32 v154, v217, v154
	v_add_f32_e32 v252, v219, v252
	v_add_f32_e32 v154, v215, v154
	v_add_f32_e32 v252, v218, v252
	v_add_f32_e32 v154, v213, v154
	v_add_f32_e32 v252, v216, v252
	v_add_f32_e32 v154, v212, v154
	v_add_f32_e32 v252, v214, v252
	v_add_f32_e32 v154, v182, v154
	v_add_f32_e32 v252, v183, v252
	v_add_f32_e32 v154, v180, v154
	v_add_f32_e32 v252, v181, v252
	v_add_f32_e32 v154, v178, v154
	v_add_f32_e32 v252, v179, v252
	v_add_f32_e32 v154, v176, v154
	v_add_f32_e32 v252, v177, v252
	v_add_f32_e32 v154, v168, v154
	v_mfma_f32_32x32x16_bf16 v[82:97], v[158:161], v[230:233], v[82:97]
	v_exp_f32_e32 v230, v165
	v_add_f32_e32 v252, v169, v252
	v_exp_f32_e32 v231, v162
	v_add_f32_e32 v154, v223, v154
	v_exp_f32_e32 v232, v163
	v_add_f32_e32 v252, v167, v252
	v_add_f32_e32 v154, v229, v154
	v_add_f32_e32 v252, v230, v252
	v_add_f32_e32 v154, v231, v154
	v_add_f32_e32 v154, v252, v154
	v_add_f32_e32 v210, v232, v154
	v_mov_b32_e32 v211, v210
	v_cvt_pk_bf16_f32 v154, v226, v228
	v_cvt_pk_bf16_f32 v155, v224, v227
	v_cvt_pk_bf16_f32 v156, v221, v225
	s_nop 1
	v_permlane32_swap_b32_e32 v210, v211
	v_cvt_pk_bf16_f32 v157, v220, v222
	v_permlane32_swap_b32_e32 v154, v156
	v_cvt_pk_bf16_f32 v158, v217, v219
	v_cvt_pk_bf16_f32 v159, v215, v218
	v_cvt_pk_bf16_f32 v160, v213, v216
	v_cvt_pk_bf16_f32 v161, v212, v214
	v_cvt_pk_bf16_f32 v162, v182, v183
	v_cvt_pk_bf16_f32 v163, v180, v181
	v_cvt_pk_bf16_f32 v164, v178, v179
	v_cvt_pk_bf16_f32 v165, v176, v177
	v_cvt_pk_bf16_f32 v166, v168, v169
	v_cvt_pk_bf16_f32 v167, v223, v167
	v_cvt_pk_bf16_f32 v168, v229, v230
	v_cvt_pk_bf16_f32 v169, v231, v232
	v_permlane32_swap_b32_e32 v155, v157
	v_permlane32_swap_b32_e32 v158, v160
	v_permlane32_swap_b32_e32 v159, v161
	v_permlane32_swap_b32_e32 v162, v164
	v_permlane32_swap_b32_e32 v163, v165
	v_permlane32_swap_b32_e32 v166, v168
	v_permlane32_swap_b32_e32 v167, v169
	s_lshl_b32 s10, s2, 14
	s_add_i32 s9, s10, 0
	v_add_u32_e32 v176, s9, v201
	s_lshl_b32 s6, s2, 13
	s_waitcnt vmcnt(0)
; #define SBAR() __builtin_amdgcn_sched_barrier(0)
; template <int D0> __device__ __forceinline__ void pv_one(f32x16& od, int vb, bf16x8 pa0, bf16x8 pa1, bf16x8 pa2, bf16x8 pa3) {
;   const s16x4 l0 = tr_read<v_rd_off(D0, 0, 0)>(vb), h0 = tr_read<v_rd_off(D0, 0, 1)>(vb), l1 = tr_read<v_rd_off(D0, 1, 0)>(vb), h1 = tr_read<v_rd_off(D0, 1, 1)>(vb);
;   const s16x4 l2 = tr_read<v_rd_off(D0, 2, 0)>(vb), h2 = tr_read<v_rd_off(D0, 2, 1)>(vb), l3 = tr_read<v_rd_off(D0, 3, 0)>(vb), h3 = tr_read<v_rd_off(D0, 3, 1)>(vb);
;   asm volatile("s_waitcnt lgkmcnt(0)" ::: "memory"); SBAR();
;     ...
;   od = __builtin_amdgcn_mfma_f32_32x32x16_bf16(pa0, PK(l0, h0), od, 0, 0, 0);
;   od = __builtin_amdgcn_mfma_f32_32x32x16_bf16(pa1, PK(l1, h1), od, 0, 0, 0);
;   od = __builtin_amdgcn_mfma_f32_32x32x16_bf16(pa2, PK(l2, h2), od, 0, 0, 0);
;   od = __builtin_amdgcn_mfma_f32_32x32x16_bf16(pa3, PK(l3, h3), od, 0, 0, 0);
;     ...
; }
	s_waitcnt vmcnt(4)
	ds_write_b128 v176, v[134:137]
	v_add_u32_e32 v134, s9, v202
	s_add_i32 s9, s9, s6
	s_waitcnt vmcnt(3)
	ds_write_b128 v134, v[138:141]
	v_add_u32_e32 v134, s9, v203
	s_waitcnt vmcnt(2)
	ds_write_b128 v134, v[142:145] offset:49152
	s_waitcnt vmcnt(1)
	ds_write_b128 v134, v[146:149] offset:61440
	v_add_u32_e32 v134, s9, v204
	v_lshl_add_u64 v[176:177], s[94:95], 0, v[174:175]
	s_mov_b32 s6, 0x198c0000
	s_waitcnt vmcnt(0)
	ds_write_b128 v134, v[150:153] offset:49152
	v_add_co_u32_e32 v134, vcc, s6, v176
	s_mov_b32 s6, 0x198e0000
	s_nop 0
	v_addc_co_u32_e32 v135, vcc, 0, v177, vcc
	v_add_co_u32_e32 v138, vcc, s6, v176
	s_mov_b32 s6, 0x150c0000
	s_nop 0
	v_addc_co_u32_e32 v139, vcc, 0, v177, vcc
	v_add_co_u32_e32 v142, vcc, s6, v176
	s_mov_b32 s6, 0x150e0000
	s_nop 0
	v_addc_co_u32_e32 v143, vcc, 0, v177, vcc
	v_add_co_u32_e32 v146, vcc, s6, v176
	v_lshl_add_u64 v[178:179], s[94:95], 0, v[172:173]
	s_nop 0
	v_addc_co_u32_e32 v147, vcc, 0, v177, vcc
	s_mov_b32 s6, 0x9906000
	v_add_co_u32_e32 v150, vcc, s6, v178
	global_load_dwordx4 v[134:137], v[134:135], off
	s_nop 0
	global_load_dwordx4 v[138:141], v[138:139], off
	v_addc_co_u32_e32 v151, vcc, 0, v179, vcc
	global_load_dwordx4 v[142:145], v[142:143], off
	s_nop 0
	global_load_dwordx4 v[146:149], v[146:147], off
	s_nop 0
	global_load_dwordx4 v[150:153], v[150:151], off
	v_lshl_add_u32 v224, s48, 14, v196
	ds_read_b64_tr_b16 v[180:181], v224 offset:0
	ds_read_b64_tr_b16 v[182:183], v224 offset:0x800
	ds_read_b64_tr_b16 v[212:213], v224 offset:0x1000
	ds_read_b64_tr_b16 v[214:215], v224 offset:0x1800
	ds_read_b64_tr_b16 v[216:217], v224 offset:0x2000
	ds_read_b64_tr_b16 v[218:219], v224 offset:0x2800
	ds_read_b64_tr_b16 v[220:221], v224 offset:0x3000
	ds_read_b64_tr_b16 v[222:223], v224 offset:0x3800
	s_waitcnt lgkmcnt(6)
	s_nop 0
	v_mfma_f32_32x32x16_bf16 v[2:17], v[154:157], v[180:183], v[2:17]
	ds_read_b64_tr_b16 v[180:181], v224 offset:0x200
	ds_read_b64_tr_b16 v[182:183], v224 offset:0xa00
	s_waitcnt lgkmcnt(6)
	v_mfma_f32_32x32x16_bf16 v[2:17], v[158:161], v[212:215], v[2:17]
	ds_read_b64_tr_b16 v[212:213], v224 offset:0x1200
	ds_read_b64_tr_b16 v[214:215], v224 offset:0x1a00
	s_waitcnt lgkmcnt(6)
	v_mfma_f32_32x32x16_bf16 v[2:17], v[162:165], v[216:219], v[2:17]
	ds_read_b64_tr_b16 v[216:217], v224 offset:0x2200
	ds_read_b64_tr_b16 v[218:219], v224 offset:0x2a00
	s_waitcnt lgkmcnt(6)
	v_mfma_f32_32x32x16_bf16 v[2:17], v[166:169], v[220:223], v[2:17]
	ds_read_b64_tr_b16 v[220:221], v224 offset:0x3200
	ds_read_b64_tr_b16 v[222:223], v224 offset:0x3a00
	s_waitcnt lgkmcnt(6)
	v_mfma_f32_32x32x16_bf16 v[50:65], v[154:157], v[180:183], v[50:65]
	ds_read_b64_tr_b16 v[180:181], v224 offset:0x400
	ds_read_b64_tr_b16 v[182:183], v224 offset:0xc00
	s_waitcnt lgkmcnt(6)
	v_mfma_f32_32x32x16_bf16 v[50:65], v[158:161], v[212:215], v[50:65]
	ds_read_b64_tr_b16 v[212:213], v224 offset:0x1400
	ds_read_b64_tr_b16 v[214:215], v224 offset:0x1c00
	s_waitcnt lgkmcnt(6)
	v_mfma_f32_32x32x16_bf16 v[50:65], v[162:165], v[216:219], v[50:65]
	ds_read_b64_tr_b16 v[216:217], v224 offset:0x2400
	ds_read_b64_tr_b16 v[218:219], v224 offset:0x2c00
	s_waitcnt lgkmcnt(6)
	v_mfma_f32_32x32x16_bf16 v[50:65], v[166:169], v[220:223], v[50:65]
	ds_read_b64_tr_b16 v[220:221], v224 offset:0x3400
	ds_read_b64_tr_b16 v[222:223], v224 offset:0x3c00
	s_waitcnt lgkmcnt(6)
	v_mfma_f32_32x32x16_bf16 v[34:49], v[154:157], v[180:183], v[34:49]
	ds_read_b64_tr_b16 v[180:181], v224 offset:0x600
	ds_read_b64_tr_b16 v[182:183], v224 offset:0xe00
	s_waitcnt lgkmcnt(6)
	v_mfma_f32_32x32x16_bf16 v[34:49], v[158:161], v[212:215], v[34:49]
	ds_read_b64_tr_b16 v[212:213], v224 offset:0x1600
	ds_read_b64_tr_b16 v[214:215], v224 offset:0x1e00
	s_waitcnt lgkmcnt(6)
	v_mfma_f32_32x32x16_bf16 v[34:49], v[162:165], v[216:219], v[34:49]
	ds_read_b64_tr_b16 v[216:217], v224 offset:0x2600
	ds_read_b64_tr_b16 v[218:219], v224 offset:0x2e00
	s_waitcnt lgkmcnt(6)
	v_mfma_f32_32x32x16_bf16 v[34:49], v[166:169], v[220:223], v[34:49]
	ds_read_b64_tr_b16 v[220:221], v224 offset:0x3600
	ds_read_b64_tr_b16 v[222:223], v224 offset:0x3e00
	s_waitcnt lgkmcnt(6)
	v_mfma_f32_32x32x16_bf16 v[18:33], v[154:157], v[180:183], v[18:33]
	v_max_f32_e32 v154, v83, v83
	v_max_f32_e32 v155, v82, v82
	v_max_f32_e32 v154, v155, v154
	v_max3_f32 v154, v154, v84, v85
	v_max3_f32 v154, v154, v86, v87
	v_max3_f32 v154, v154, v88, v89
	v_max3_f32 v154, v154, v90, v91
	v_max3_f32 v154, v154, v92, v93
	v_max3_f32 v154, v154, v94, v95
	s_waitcnt lgkmcnt(4)
	v_mfma_f32_32x32x16_bf16 v[18:33], v[158:161], v[212:215], v[18:33]
	v_max3_f32 v154, v154, v96, v97
	v_max3_f32 v154, v154, v66, v67
	v_max3_f32 v154, v154, v68, v69
	v_max3_f32 v154, v154, v70, v71
	v_max3_f32 v154, v154, v72, v73
	v_max3_f32 v154, v154, v74, v75
	v_max3_f32 v154, v154, v76, v77
	v_max3_f32 v154, v154, v78, v79
	s_waitcnt lgkmcnt(2)
	v_mfma_f32_32x32x16_bf16 v[18:33], v[162:165], v[216:219], v[18:33]
	v_max3_f32 v154, v154, v80, v81
	v_mov_b32_e32 v155, v154
	s_nop 1
	v_permlane32_swap_b32_e32 v154, v155
	v_max_f32_e32 v155, v155, v155
	v_max_f32_e32 v154, v154, v154
	v_max_f32_e32 v154, v154, v155
	v_sub_f32_e32 v155, v154, v209
	v_cmp_ge_f32_e32 vcc, s49, v155
	v_max_f32_e32 v155, v209, v209
	v_max_f32_e32 v154, v155, v154
	s_waitcnt lgkmcnt(0)
	v_mfma_f32_32x32x16_bf16 v[18:33], v[166:169], v[220:223], v[18:33]
	v_sub_f32_e32 v155, v209, v154
	v_mul_f32_e32 v155, 0x3dd53b94, v155
	v_exp_f32_e32 v155, v155
	s_cmp_eq_u64 vcc, exec
	s_cselect_b64 s[40:41], -1, 0
	s_waitcnt lgkmcnt(0)
	s_barrier
	v_cndmask_b32_e64 v223, v155, 1.0, s[40:41]
	v_cmp_gt_f32_e32 vcc, 1.0, v223
	s_cbranch_vccz .LBB0_55
; template <int DQK> __device__ __forceinline__ void partialSM(f32x16& p0, f32x16& p1, float& m_reg, float& mn, float& alpha) {
;     ...
;   else { mn = fmaxf(m_reg, pmax); alpha = __builtin_amdgcn_exp2f((m_reg - mn) * C); m_reg = mn; }
;   float mnC = -mn * C;
; #pragma unroll
;   for (int r = 0; r < 16; ++r) p0[r] = fmaf(p0[r], C, mnC);
; #pragma unroll
;   for (int r = 0; r < 16; ++r) p1[r] = fmaf(p1[r], C, mnC);
; #pragma unroll
;   for (int r = 0; r < 16; ++r) p0[r] = __builtin_amdgcn_exp2f(p0[r]);
	s_and_saveexec_b64 s[6:7], s[38:39]
	ds_write_b32 v198, v223 offset:128
	s_or_b64 exec, exec, s[6:7]
	s_waitcnt lgkmcnt(0)
	v_add_u32_e32 v155, v195, v170
	ds_read_b128 v[156:159], v155 offset:224
	ds_read_b128 v[160:163], v155 offset:192
	ds_read_b128 v[164:167], v155 offset:160
	ds_read_b128 v[180:183], v155 offset:128
	s_waitcnt lgkmcnt(3)
	v_pk_mul_f32 v[14:15], v[14:15], v[156:157]
	s_waitcnt lgkmcnt(2)
	v_pk_mul_f32 v[10:11], v[10:11], v[160:161]
	s_waitcnt lgkmcnt(1)
	v_pk_mul_f32 v[6:7], v[6:7], v[164:165]
	v_pk_mul_f32 v[16:17], v[16:17], v[158:159]
	v_pk_mul_f32 v[12:13], v[12:13], v[162:163]
	v_pk_mul_f32 v[8:9], v[8:9], v[166:167]
	s_waitcnt lgkmcnt(0)
	v_pk_mul_f32 v[4:5], v[4:5], v[182:183]
	v_pk_mul_f32 v[2:3], v[2:3], v[180:181]
	v_pk_mul_f32 v[62:63], v[62:63], v[156:157]
	v_pk_mul_f32 v[58:59], v[58:59], v[160:161]
	v_pk_mul_f32 v[54:55], v[54:55], v[164:165]
	v_pk_mul_f32 v[64:65], v[64:65], v[158:159]
	v_pk_mul_f32 v[60:61], v[60:61], v[162:163]
	v_pk_mul_f32 v[56:57], v[56:57], v[166:167]
	v_pk_mul_f32 v[52:53], v[52:53], v[182:183]
	v_pk_mul_f32 v[50:51], v[50:51], v[180:181]
	v_pk_mul_f32 v[46:47], v[46:47], v[156:157]
	v_pk_mul_f32 v[42:43], v[42:43], v[160:161]
	v_pk_mul_f32 v[38:39], v[38:39], v[164:165]
	v_pk_mul_f32 v[48:49], v[48:49], v[158:159]
	v_pk_mul_f32 v[44:45], v[44:45], v[162:163]
	v_pk_mul_f32 v[40:41], v[40:41], v[166:167]
	v_pk_mul_f32 v[36:37], v[36:37], v[182:183]
	v_pk_mul_f32 v[34:35], v[34:35], v[180:181]
	v_pk_mul_f32 v[30:31], v[30:31], v[156:157]
	v_pk_mul_f32 v[26:27], v[26:27], v[160:161]
	v_pk_mul_f32 v[22:23], v[22:23], v[164:165]
	v_pk_mul_f32 v[32:33], v[32:33], v[158:159]
	v_pk_mul_f32 v[28:29], v[28:29], v[162:163]
	v_pk_mul_f32 v[24:25], v[24:25], v[166:167]
	v_pk_mul_f32 v[20:21], v[20:21], v[182:183]
	v_pk_mul_f32 v[18:19], v[18:19], v[180:181]
.LBB0_55:
	v_cndmask_b32_e64 v180, v154, v209, s[40:41]
	v_mul_f32_e32 v213, 0xbdd53b94, v180
	v_fmamk_f32 v82, v82, 0x3dd53b94, v213
	v_fmamk_f32 v83, v83, 0x3dd53b94, v213
	v_fmamk_f32 v84, v84, 0x3dd53b94, v213
	v_fmamk_f32 v90, v90, 0x3dd53b94, v213
	v_fmamk_f32 v91, v91, 0x3dd53b94, v213
	v_fmamk_f32 v92, v92, 0x3dd53b94, v213
	v_fmamk_f32 v93, v93, 0x3dd53b94, v213
	v_fmamk_f32 v94, v94, 0x3dd53b94, v213
	v_exp_f32_e32 v165, v82
	v_exp_f32_e32 v168, v83
	v_exp_f32_e32 v169, v84
	v_exp_f32_e32 v162, v90
	v_exp_f32_e32 v163, v91
	v_exp_f32_e32 v164, v92
	v_exp_f32_e32 v166, v93
	v_exp_f32_e32 v167, v94
	s_add_i32 s6, s2, 1
	s_cmp_lg_u32 s2, 2
	v_fmamk_f32 v85, v85, 0x3dd53b94, v213
	v_fmamk_f32 v86, v86, 0x3dd53b94, v213
	v_fmamk_f32 v87, v87, 0x3dd53b94, v213
	v_fmamk_f32 v88, v88, 0x3dd53b94, v213
	v_fmamk_f32 v89, v89, 0x3dd53b94, v213
	v_fmamk_f32 v95, v95, 0x3dd53b94, v213
	v_fmamk_f32 v96, v96, 0x3dd53b94, v213
	v_fmamk_f32 v97, v97, 0x3dd53b94, v213
	v_fmamk_f32 v229, v77, 0x3dd53b94, v213
	v_fmamk_f32 v230, v78, 0x3dd53b94, v213
	s_cselect_b32 s12, s6, 0
	v_fmamk_f32 v217, v66, 0x3dd53b94, v213
	v_fmamk_f32 v218, v67, 0x3dd53b94, v213
	v_fmamk_f32 v219, v68, 0x3dd53b94, v213
	v_fmamk_f32 v220, v69, 0x3dd53b94, v213
	v_fmamk_f32 v221, v70, 0x3dd53b94, v213
	v_fmamk_f32 v222, v71, 0x3dd53b94, v213
	v_fmamk_f32 v224, v72, 0x3dd53b94, v213
	v_fmamk_f32 v225, v73, 0x3dd53b94, v213
	v_fmamk_f32 v226, v74, 0x3dd53b94, v213
	v_fmamk_f32 v227, v75, 0x3dd53b94, v213
	v_fmamk_f32 v228, v76, 0x3dd53b94, v213
	v_fmamk_f32 v231, v79, 0x3dd53b94, v213
	v_fmamk_f32 v232, v80, 0x3dd53b94, v213
	v_fmac_f32_e32 v213, 0x3dd53b94, v81
	v_exp_f32_e32 v183, v85
	v_exp_f32_e32 v209, v86
	v_exp_f32_e32 v214, v87
	v_exp_f32_e32 v215, v88
	v_exp_f32_e32 v216, v89
	v_exp_f32_e32 v181, v95
	v_exp_f32_e32 v182, v96
	v_exp_f32_e32 v212, v97
	v_add_u32_e32 v233, s9, v207
	v_add_u32_e32 v242, s9, v200
	ds_read_b128 v[154:157], v233 offset:49152
	ds_read_b128 v[158:161], v233 offset:61440
	ds_read_b128 v[66:69], v242 offset:61440
	ds_read_b128 v[70:73], v242 offset:49152
	v_add_u32_e32 v243, s9, v205
	v_add_u32_e32 v246, s9, v206
	s_waitcnt lgkmcnt(0)
	v_mfma_f32_32x32x16_bf16 v[82:97], v[70:73], v[130:133], 0
	v_exp_f32_e32 v217, v217
	v_exp_f32_e32 v218, v218
	v_exp_f32_e32 v219, v219
	v_exp_f32_e32 v220, v220
	v_exp_f32_e32 v221, v221
	v_exp_f32_e32 v222, v222
	v_exp_f32_e32 v224, v224
	v_mfma_f32_32x32x16_bf16 v[66:81], v[66:69], v[130:133], 0
	ds_read_b128 v[234:237], v243 offset:49152
	ds_read_b128 v[238:241], v243 offset:61440
	v_exp_f32_e32 v225, v225
	v_exp_f32_e32 v226, v226
	v_exp_f32_e32 v227, v227
	v_exp_f32_e32 v228, v228
	v_exp_f32_e32 v231, v231
	v_exp_f32_e32 v232, v232
	v_mfma_f32_32x32x16_bf16 v[66:81], v[158:161], v[126:129], v[66:81]
	v_exp_f32_e32 v213, v213
	v_mfma_f32_32x32x16_bf16 v[82:97], v[154:157], v[126:129], v[82:97]
	ds_read_b128 v[154:157], v246 offset:49152
	ds_read_b128 v[158:161], v246 offset:61440
	s_waitcnt lgkmcnt(2)
	v_mfma_f32_32x32x16_bf16 v[66:81], v[238:241], v[122:125], v[66:81]
	v_mfma_f32_32x32x16_bf16 v[82:97], v[234:237], v[122:125], v[82:97]
	ds_read_b128 v[234:237], v242 offset:49280
	ds_read_b128 v[238:241], v242 offset:61568
	s_waitcnt lgkmcnt(2)
	v_mfma_f32_32x32x16_bf16 v[66:81], v[158:161], v[118:121], v[66:81]
	v_mfma_f32_32x32x16_bf16 v[82:97], v[154:157], v[118:121], v[82:97]
	ds_read_b128 v[154:157], v233 offset:49280
	ds_read_b128 v[158:161], v233 offset:61568
	s_waitcnt lgkmcnt(2)
; __device__ __forceinline__ void finishSM(f32x16& p0, f32x16& p1, float alpha, float& l_reg, bf16x8& pa0, bf16x8& pa1, bf16x8& pa2, bf16x8& pa3) {
; #pragma unroll
;   for (int r = 0; r < 16; ++r) p1[r] = __builtin_amdgcn_exp2f(p1[r]);
;   float ps = 0;
; #pragma unroll
;   for (int r = 0; r < 16; ++r) ps += p0[r];
; #pragma unroll
;   for (int r = 0; r < 16; ++r) ps += p1[r];
;   { auto rr = __builtin_amdgcn_permlane32_swap(__float_as_uint(ps), __float_as_uint(ps), false, false);
;     ps = __uint_as_float(rr[0]) + __uint_as_float(rr[1]); }
;   l_reg = l_reg * alpha + ps;
;     ...
;   PK4(p0, 0, pa0); PK4(p0, 8, pa1); PK4(p1, 0, pa2); PK4(p1, 8, pa3);
;     ...
; }
; template <int DQK, int KW, int QSP> __device__ __forceinline__ void qkt(f32x16& p0, f32x16& p1, const char* Ks, const int (&kb)[4], const bf16x8* qr, const char* qsp, const f32x16& cinit) {
;   p0 = cinit; p1 = cinit;
;   constexpr int N = DQK / 16;
;     ...
;   bf16x8 f0[2], f1[2];
;   f0[0] = KRD(0, 1); f1[0] = KRD(0, 0);
; #pragma unroll
;   for (int d0 = 0; d0 < N; ++d0) {
;     if (d0 + 1 < N) { f0[(d0 + 1) & 1] = KRD(d0 + 1, 1); f1[(d0 + 1) & 1] = KRD(d0 + 1, 0); }
;     __builtin_amdgcn_sched_barrier(0x406);
;     bf16x8 qf;
;     if constexpr (QSP > 0) { if (d0 >= N - QSP) qf = *reinterpret_cast<const bf16x8*>(qsp + (d0 - (N - QSP)) * 1024); else qf = qr[d0]; } else qf = qr[d0];
;     p0 = __builtin_amdgcn_mfma_f32_32x32x16_bf16(f0[d0 & 1], qf, p0, 0, 0, 0);
;     p1 = __builtin_amdgcn_mfma_f32_32x32x16_bf16(f1[d0 & 1], qf, p1, 0, 0, 0);
;     __builtin_amdgcn_sched_barrier(0x406); }
;     ...
; }
	v_mfma_f32_32x32x16_bf16 v[66:81], v[238:241], v[114:117], v[66:81]
	v_mfma_f32_32x32x16_bf16 v[82:97], v[234:237], v[114:117], v[82:97]
	ds_read_b128 v[234:237], v243 offset:49280
	ds_read_b128 v[238:241], v243 offset:61568
	s_waitcnt lgkmcnt(2)
	v_mfma_f32_32x32x16_bf16 v[66:81], v[158:161], v[110:113], v[66:81]
	v_mfma_f32_32x32x16_bf16 v[82:97], v[154:157], v[110:113], v[82:97]
	ds_read_b128 v[154:157], v246 offset:49280
	ds_read_b128 v[158:161], v246 offset:61568
	s_waitcnt lgkmcnt(2)
	v_mfma_f32_32x32x16_bf16 v[66:81], v[238:241], v[106:109], v[66:81]
	v_mfma_f32_32x32x16_bf16 v[82:97], v[234:237], v[106:109], v[82:97]
	ds_read_b128 v[234:237], v242 offset:49408
	ds_read_b128 v[238:241], v242 offset:61696
	s_waitcnt lgkmcnt(2)
	v_mfma_f32_32x32x16_bf16 v[66:81], v[158:161], v[102:105], v[66:81]
	v_mfma_f32_32x32x16_bf16 v[82:97], v[154:157], v[102:105], v[82:97]
	ds_read_b128 v[154:157], v233 offset:49408
	ds_read_b128 v[158:161], v233 offset:61696
	v_exp_f32_e32 v233, v229
	s_waitcnt lgkmcnt(2)
	v_mfma_f32_32x32x16_bf16 v[66:81], v[238:241], v[98:101], v[66:81]
	v_mfma_f32_32x32x16_bf16 v[82:97], v[234:237], v[98:101], v[82:97]
	ds_read_b128 v[234:237], v243 offset:49408
	ds_read_b128 v[238:241], v243 offset:61696
	s_waitcnt lgkmcnt(2)
	v_mfma_f32_32x32x16_bf16 v[66:81], v[158:161], v[248:251], v[66:81]
	v_mfma_f32_32x32x16_bf16 v[82:97], v[154:157], v[248:251], v[82:97]
	ds_read_b128 v[158:161], v246 offset:49408
	ds_read_b128 v[154:157], v246 offset:61696
	ds_read_b128 v[242:245], v197 offset:1024
	s_waitcnt lgkmcnt(0)
	v_mfma_f32_32x32x16_bf16 v[66:81], v[238:241], v[242:245], v[66:81]
	v_mfma_f32_32x32x16_bf16 v[82:97], v[234:237], v[242:245], v[82:97]
	ds_read_b128 v[234:237], v197 offset:2048
	s_waitcnt lgkmcnt(0)
	v_mfma_f32_32x32x16_bf16 v[66:81], v[154:157], v[234:237], v[66:81]
	v_add_f32_e32 v154, 0, v165
	v_add_f32_e32 v252, 0, v168
	v_add_f32_e32 v154, v169, v154
	v_add_f32_e32 v252, v183, v252
	v_add_f32_e32 v154, v209, v154
	v_add_f32_e32 v252, v214, v252
	v_add_f32_e32 v154, v215, v154
	v_add_f32_e32 v252, v216, v252
	v_add_f32_e32 v154, v162, v154
	v_add_f32_e32 v252, v163, v252
	v_add_f32_e32 v154, v164, v154
	v_add_f32_e32 v252, v166, v252
	v_add_f32_e32 v154, v167, v154
	v_add_f32_e32 v252, v181, v252
	v_add_f32_e32 v154, v182, v154
	v_add_f32_e32 v252, v212, v252
	v_add_f32_e32 v154, v217, v154
	v_add_f32_e32 v252, v218, v252
	v_add_f32_e32 v154, v219, v154
	v_add_f32_e32 v252, v220, v252
	v_add_f32_e32 v154, v221, v154
	v_add_f32_e32 v252, v222, v252
	v_add_f32_e32 v154, v224, v154
	v_add_f32_e32 v252, v225, v252
	v_mfma_f32_32x32x16_bf16 v[82:97], v[158:161], v[234:237], v[82:97]
	v_exp_f32_e32 v234, v230
	v_add_f32_e32 v154, v226, v154
	v_add_f32_e32 v252, v227, v252
	v_add_f32_e32 v154, v228, v154
	v_add_f32_e32 v252, v233, v252
	v_add_f32_e32 v154, v234, v154
	v_add_f32_e32 v252, v231, v252
	v_add_f32_e32 v154, v232, v154
	v_add_f32_e32 v154, v252, v154
	v_add_f32_e32 v229, v213, v154
	v_mov_b32_e32 v230, v229
	v_cvt_pk_bf16_f32 v154, v165, v168
	v_cvt_pk_bf16_f32 v155, v169, v183
	v_cvt_pk_bf16_f32 v156, v209, v214
	v_cvt_pk_bf16_f32 v157, v215, v216
	v_cvt_pk_bf16_f32 v158, v162, v163
	v_cvt_pk_bf16_f32 v159, v164, v166
	v_cvt_pk_bf16_f32 v160, v167, v181
	v_cvt_pk_bf16_f32 v161, v182, v212
	v_cvt_pk_bf16_f32 v162, v217, v218
	v_cvt_pk_bf16_f32 v163, v219, v220
	v_cvt_pk_bf16_f32 v164, v221, v222
	v_cvt_pk_bf16_f32 v165, v224, v225
	v_cvt_pk_bf16_f32 v166, v226, v227
	v_cvt_pk_bf16_f32 v167, v228, v233
	v_cvt_pk_bf16_f32 v168, v234, v231
	v_cvt_pk_bf16_f32 v169, v232, v213
	s_nop 1
	v_permlane32_swap_b32_e32 v229, v230
	v_permlane32_swap_b32_e32 v154, v156
	v_permlane32_swap_b32_e32 v155, v157
	v_permlane32_swap_b32_e32 v158, v160
	v_permlane32_swap_b32_e32 v159, v161
	v_permlane32_swap_b32_e32 v162, v164
	v_permlane32_swap_b32_e32 v163, v165
	v_permlane32_swap_b32_e32 v166, v168
	v_permlane32_swap_b32_e32 v167, v169
	s_lshl_b32 s11, s12, 14
	s_add_i32 s13, s11, 0
	v_add_u32_e32 v181, s13, v201
	s_lshl_b32 s6, s12, 13
	s_waitcnt vmcnt(0)
	s_waitcnt vmcnt(4)
	ds_write_b128 v181, v[134:137]
	v_add_u32_e32 v181, s13, v202
	s_add_i32 s13, s13, s6
	s_cmp_ge_u32 s31, s33
	s_waitcnt vmcnt(3)
	ds_write_b128 v181, v[138:141]
	v_add_u32_e32 v181, s13, v203
	s_cselect_b64 s[6:7], -1, 0
	s_waitcnt vmcnt(2)
	ds_write_b128 v181, v[142:145] offset:49152
	s_waitcnt vmcnt(1)
	ds_write_b128 v181, v[146:149] offset:61440
	v_add_u32_e32 v181, s13, v204
	s_and_b64 vcc, exec, s[6:7]
	s_waitcnt vmcnt(0)
	ds_write_b128 v181, v[150:153] offset:49152
	s_cbranch_vccnz .LBB0_57
	v_add_co_u32_e32 v134, vcc, 0x19900000, v176
	s_nop 1
	v_addc_co_u32_e32 v135, vcc, 0, v177, vcc
	v_add_co_u32_e32 v138, vcc, 0x19920000, v176
	s_nop 1
	v_addc_co_u32_e32 v139, vcc, 0, v177, vcc
	v_add_co_u32_e32 v142, vcc, 0x15100000, v176
	global_load_dwordx4 v[134:137], v[134:135], off
	s_nop 0
	global_load_dwordx4 v[138:141], v[138:139], off
	v_addc_co_u32_e32 v143, vcc, 0, v177, vcc
	v_add_co_u32_e32 v146, vcc, 0x15120000, v176
	s_nop 1
	v_addc_co_u32_e32 v147, vcc, 0, v177, vcc
	v_add_co_u32_e32 v150, vcc, 0x9908000, v178
	global_load_dwordx4 v[142:145], v[142:143], off
	s_nop 0
	global_load_dwordx4 v[146:149], v[146:147], off
	v_addc_co_u32_e32 v151, vcc, 0, v179, vcc
	global_load_dwordx4 v[150:153], v[150:151], off

; __device__ __forceinline__ void finishSM(f32x16& p0, f32x16& p1, float alpha, float& l_reg, bf16x8& pa0, bf16x8& pa1, bf16x8& pa2, bf16x8& pa3) {
; #pragma unroll
;   for (int r = 0; r < 16; ++r) p1[r] = __builtin_amdgcn_exp2f(p1[r]);
;   float ps = 0;
; #pragma unroll
;   for (int r = 0; r < 16; ++r) ps += p0[r];
; #pragma unroll
;   for (int r = 0; r < 16; ++r) ps += p1[r];
;   { auto rr = __builtin_amdgcn_permlane32_swap(__float_as_uint(ps), __float_as_uint(ps), false, false);
;     ps = __uint_as_float(rr[0]) + __uint_as_float(rr[1]); }
;   l_reg = l_reg * alpha + ps;
;     ...
;   PK4(p0, 0, pa0); PK4(p0, 8, pa1); PK4(p1, 0, pa2); PK4(p1, 8, pa3);
;     ...
; }
; template <int DQK, int KW, int QSP> __device__ __forceinline__ void qkt(f32x16& p0, f32x16& p1, const char* Ks, const int (&kb)[4], const bf16x8* qr, const char* qsp, const f32x16& cinit) {
;   p0 = cinit; p1 = cinit;
;   constexpr int N = DQK / 16;
;     ...
;   bf16x8 f0[2], f1[2];
;   f0[0] = KRD(0, 1); f1[0] = KRD(0, 0);
; #pragma unroll
;   for (int d0 = 0; d0 < N; ++d0) {
;     if (d0 + 1 < N) { f0[(d0 + 1) & 1] = KRD(d0 + 1, 1); f1[(d0 + 1) & 1] = KRD(d0 + 1, 0); }
;     __builtin_amdgcn_sched_barrier(0x406);
;     bf16x8 qf;
;     if constexpr (QSP > 0) { if (d0 >= N - QSP) qf = *reinterpret_cast<const bf16x8*>(qsp + (d0 - (N - QSP)) * 1024); else qf = qr[d0]; } else qf = qr[d0];
;     p0 = __builtin_amdgcn_mfma_f32_32x32x16_bf16(f0[d0 & 1], qf, p0, 0, 0, 0);
;     p1 = __builtin_amdgcn_mfma_f32_32x32x16_bf16(f1[d0 & 1], qf, p1, 0, 0, 0);
;     __builtin_amdgcn_sched_barrier(0x406); }
;     ...
; }
.LBB0_286:
	s_lshl_b32 s8, s30, 14
	s_add_i32 s6, s8, 0
	v_add_u32_e32 v208, s6, v163
	v_add_u32_e32 v209, s6, v158
	ds_read_b128 v[168:171], v208 offset:49152
	ds_read_b128 v[196:199], v208 offset:57344
	ds_read_b128 v[66:69], v209 offset:57344
	ds_read_b128 v[70:73], v209 offset:49152
	v_add_u32_e32 v212, s6, v164
	v_add_u32_e32 v213, s6, v165
	s_waitcnt lgkmcnt(0)
	v_mfma_f32_32x32x16_bf16 v[82:97], v[70:73], v[102:105], 0
	v_exp_f32_e32 v144, v144
	v_exp_f32_e32 v145, v145
	v_exp_f32_e32 v142, v142
	v_exp_f32_e32 v143, v143
	v_exp_f32_e32 v140, v140
	v_exp_f32_e32 v141, v141
	v_mfma_f32_32x32x16_bf16 v[66:81], v[66:69], v[102:105], 0
	ds_read_b128 v[200:203], v212 offset:49152
	ds_read_b128 v[204:207], v212 offset:57344
	v_mfma_f32_32x32x16_bf16 v[82:97], v[168:171], v[110:113], v[82:97]
	v_mfma_f32_32x32x16_bf16 v[66:81], v[196:199], v[110:113], v[66:81]
	ds_read_b128 v[168:171], v213 offset:49152
	ds_read_b128 v[196:199], v213 offset:57344
	s_waitcnt lgkmcnt(3)
	v_mfma_f32_32x32x16_bf16 v[82:97], v[200:203], v[106:109], v[82:97]
	s_waitcnt lgkmcnt(2)
	v_mfma_f32_32x32x16_bf16 v[66:81], v[204:207], v[106:109], v[66:81]
	ds_read_b128 v[200:203], v209 offset:49280
	ds_read_b128 v[204:207], v209 offset:57472
	s_waitcnt lgkmcnt(3)
	v_mfma_f32_32x32x16_bf16 v[82:97], v[168:171], v[98:101], v[82:97]
	s_waitcnt lgkmcnt(2)
	v_mfma_f32_32x32x16_bf16 v[66:81], v[196:199], v[98:101], v[66:81]
	ds_read_b128 v[168:171], v208 offset:49280
	ds_read_b128 v[196:199], v208 offset:57472
	s_waitcnt lgkmcnt(3)
	v_mfma_f32_32x32x16_bf16 v[82:97], v[200:203], v[220:223], v[82:97]
	s_waitcnt lgkmcnt(2)
	v_mfma_f32_32x32x16_bf16 v[66:81], v[204:207], v[220:223], v[66:81]
	ds_read_b128 v[200:203], v212 offset:49280
	ds_read_b128 v[204:207], v212 offset:57472
	s_waitcnt lgkmcnt(3)
	v_mfma_f32_32x32x16_bf16 v[82:97], v[168:171], v[224:227], v[82:97]
	s_waitcnt lgkmcnt(2)
	v_mfma_f32_32x32x16_bf16 v[66:81], v[196:199], v[224:227], v[66:81]
	ds_read_b128 v[168:171], v213 offset:49280
	ds_read_b128 v[196:199], v213 offset:57472
	s_waitcnt lgkmcnt(3)
	v_mfma_f32_32x32x16_bf16 v[82:97], v[200:203], v[228:231], v[82:97]
	s_waitcnt lgkmcnt(2)
	v_mfma_f32_32x32x16_bf16 v[66:81], v[204:207], v[228:231], v[66:81]
	s_waitcnt lgkmcnt(0)
	v_mfma_f32_32x32x16_bf16 v[82:97], v[168:171], v[232:235], v[82:97]
	v_exp_f32_e32 v170, v138
	v_exp_f32_e32 v171, v139
	v_mfma_f32_32x32x16_bf16 v[66:81], v[196:199], v[232:235], v[66:81]
	v_exp_f32_e32 v202, v130
	v_add_f32_e32 v130, 0, v193
	v_add_f32_e32 v252, 0, v195
	v_add_f32_e32 v130, v183, v130
	v_add_f32_e32 v252, v194, v252
	v_add_f32_e32 v130, v181, v130
	v_add_f32_e32 v252, v192, v252
	v_add_f32_e32 v130, v180, v130
	v_add_f32_e32 v252, v182, v252
	v_add_f32_e32 v130, v177, v130
	v_add_f32_e32 v252, v179, v252
	v_add_f32_e32 v130, v175, v130
	v_add_f32_e32 v252, v178, v252
	v_add_f32_e32 v130, v173, v130
	v_add_f32_e32 v252, v176, v252
	v_add_f32_e32 v130, v172, v130
	v_add_f32_e32 v252, v174, v252
	v_add_f32_e32 v130, v144, v130
	v_add_f32_e32 v252, v145, v252
	v_add_f32_e32 v130, v142, v130
	v_add_f32_e32 v252, v143, v252
	v_exp_f32_e32 v196, v136
	v_add_f32_e32 v130, v140, v130
	v_exp_f32_e32 v197, v137
	v_add_f32_e32 v252, v141, v252
	v_exp_f32_e32 v198, v134
	v_add_f32_e32 v130, v170, v130
	v_exp_f32_e32 v199, v135
	v_add_f32_e32 v252, v171, v252
	v_exp_f32_e32 v200, v132
	v_add_f32_e32 v130, v196, v130
	v_exp_f32_e32 v201, v133
	v_add_f32_e32 v252, v197, v252
	v_add_f32_e32 v130, v198, v130
	v_exp_f32_e32 v203, v131
	v_add_f32_e32 v252, v199, v252
	v_add_f32_e32 v130, v200, v130
	v_add_f32_e32 v252, v201, v252
	v_add_f32_e32 v130, v202, v130
	v_add_f32_e32 v130, v252, v130
	v_add_f32_e32 v168, v203, v130
	v_mov_b32_e32 v169, v168
	v_cvt_pk_bf16_f32 v130, v193, v195
	v_cvt_pk_bf16_f32 v131, v183, v194
	v_cvt_pk_bf16_f32 v132, v181, v192
	s_nop 1
	v_permlane32_swap_b32_e32 v168, v169
	v_cvt_pk_bf16_f32 v133, v180, v182
	v_permlane32_swap_b32_e32 v130, v132
	v_cvt_pk_bf16_f32 v134, v177, v179
	v_cvt_pk_bf16_f32 v135, v175, v178
	v_cvt_pk_bf16_f32 v136, v173, v176
	v_cvt_pk_bf16_f32 v137, v172, v174
	v_cvt_pk_bf16_f32 v138, v144, v145
	v_cvt_pk_bf16_f32 v139, v142, v143
	v_cvt_pk_bf16_f32 v140, v140, v141
	v_cvt_pk_bf16_f32 v141, v170, v171
	v_cvt_pk_bf16_f32 v142, v196, v197
	v_cvt_pk_bf16_f32 v143, v198, v199
	v_cvt_pk_bf16_f32 v144, v200, v201
	v_cvt_pk_bf16_f32 v145, v202, v203
	v_permlane32_swap_b32_e32 v131, v133
	v_permlane32_swap_b32_e32 v134, v136
	v_permlane32_swap_b32_e32 v135, v137
	v_permlane32_swap_b32_e32 v138, v140
	v_permlane32_swap_b32_e32 v139, v141
	v_permlane32_swap_b32_e32 v142, v144
	v_permlane32_swap_b32_e32 v143, v145
	s_lshl_b32 s28, s27, 14
	s_add_i32 s9, s28, 0
	v_add_u32_e32 v170, s9, v159
	s_waitcnt vmcnt(0)
	s_waitcnt vmcnt(3)
	ds_write_b128 v170, v[114:117]
	v_add_u32_e32 v114, s9, v160
	s_waitcnt vmcnt(1)
	ds_write_b128 v114, v[118:121]
	v_add_u32_e32 v114, s9, v161
	s_mov_b32 s6, 0xfffe8000
	s_waitcnt vmcnt(1)
	ds_write_b128 v114, v[122:125] offset:49152
	s_waitcnt vmcnt(0)
	ds_write_b128 v114, v[126:129] offset:57344
	v_add_co_u32_e32 v114, vcc, s6, v148
	s_mov_b32 s6, 0xfb7e8000
	s_nop 0
	v_addc_co_u32_e32 v115, vcc, -1, v149, vcc
	v_add_co_u32_e32 v118, vcc, s3, v148
	s_nop 1
	v_addc_co_u32_e32 v119, vcc, -1, v149, vcc
	v_add_co_u32_e32 v122, vcc, s6, v148
	s_mov_b32 s6, 0xfb7f0000
	s_nop 0
	v_addc_co_u32_e32 v123, vcc, -1, v149, vcc
	v_add_co_u32_e32 v126, vcc, s6, v148
	global_load_dwordx4 v[114:117], v[114:115], off
	s_nop 0
	global_load_dwordx4 v[118:121], v[118:119], off
	v_addc_co_u32_e32 v127, vcc, -1, v149, vcc
	global_load_dwordx4 v[122:125], v[122:123], off
	s_nop 0
	global_load_dwordx4 v[126:129], v[126:127], off
	v_lshl_add_u32 v182, s48, 14, v154
	ds_read_b64_tr_b16 v[170:171], v182 offset:0
	ds_read_b64_tr_b16 v[172:173], v182 offset:0x800
	ds_read_b64_tr_b16 v[174:175], v182 offset:0x1000
	ds_read_b64_tr_b16 v[176:177], v182 offset:0x1800
	ds_read_b64_tr_b16 v[178:179], v182 offset:0x2000
	ds_read_b64_tr_b16 v[180:181], v182 offset:0x2800
	ds_read_b64_tr_b16 v[192:193], v182 offset:0x3000
	ds_read_b64_tr_b16 v[194:195], v182 offset:0x3800
	s_waitcnt lgkmcnt(6)
; #define SBAR() __builtin_amdgcn_sched_barrier(0)
; template <int D0> __device__ __forceinline__ void pv_one(f32x16& od, int vb, bf16x8 pa0, bf16x8 pa1, bf16x8 pa2, bf16x8 pa3) {
;   const s16x4 l0 = tr_read<v_rd_off(D0, 0, 0)>(vb), h0 = tr_read<v_rd_off(D0, 0, 1)>(vb), l1 = tr_read<v_rd_off(D0, 1, 0)>(vb), h1 = tr_read<v_rd_off(D0, 1, 1)>(vb);
;   const s16x4 l2 = tr_read<v_rd_off(D0, 2, 0)>(vb), h2 = tr_read<v_rd_off(D0, 2, 1)>(vb), l3 = tr_read<v_rd_off(D0, 3, 0)>(vb), h3 = tr_read<v_rd_off(D0, 3, 1)>(vb);
;   asm volatile("s_waitcnt lgkmcnt(0)" ::: "memory"); SBAR();
;     ...
;   od = __builtin_amdgcn_mfma_f32_32x32x16_bf16(pa0, PK(l0, h0), od, 0, 0, 0);
;   od = __builtin_amdgcn_mfma_f32_32x32x16_bf16(pa1, PK(l1, h1), od, 0, 0, 0);
;   od = __builtin_amdgcn_mfma_f32_32x32x16_bf16(pa2, PK(l2, h2), od, 0, 0, 0);
;   od = __builtin_amdgcn_mfma_f32_32x32x16_bf16(pa3, PK(l3, h3), od, 0, 0, 0);
;     ...
; }
	s_nop 0
	v_mfma_f32_32x32x16_bf16 v[2:17], v[130:133], v[170:173], v[2:17]
	ds_read_b64_tr_b16 v[170:171], v182 offset:0x200
	ds_read_b64_tr_b16 v[172:173], v182 offset:0xa00
	s_waitcnt lgkmcnt(6)
	v_mfma_f32_32x32x16_bf16 v[2:17], v[134:137], v[174:177], v[2:17]
	ds_read_b64_tr_b16 v[174:175], v182 offset:0x1200
	ds_read_b64_tr_b16 v[176:177], v182 offset:0x1a00
	s_waitcnt lgkmcnt(6)
	v_mfma_f32_32x32x16_bf16 v[2:17], v[138:141], v[178:181], v[2:17]
	ds_read_b64_tr_b16 v[178:179], v182 offset:0x2200
	ds_read_b64_tr_b16 v[180:181], v182 offset:0x2a00
	s_waitcnt lgkmcnt(6)
	v_mfma_f32_32x32x16_bf16 v[2:17], v[142:145], v[192:195], v[2:17]
	ds_read_b64_tr_b16 v[192:193], v182 offset:0x3200
	ds_read_b64_tr_b16 v[194:195], v182 offset:0x3a00
	s_waitcnt lgkmcnt(6)
	v_mfma_f32_32x32x16_bf16 v[50:65], v[130:133], v[170:173], v[50:65]
	ds_read_b64_tr_b16 v[170:171], v182 offset:0x400
	ds_read_b64_tr_b16 v[172:173], v182 offset:0xc00
	s_waitcnt lgkmcnt(6)
	v_mfma_f32_32x32x16_bf16 v[50:65], v[134:137], v[174:177], v[50:65]
	ds_read_b64_tr_b16 v[174:175], v182 offset:0x1400
	ds_read_b64_tr_b16 v[176:177], v182 offset:0x1c00
	s_waitcnt lgkmcnt(6)
	v_mfma_f32_32x32x16_bf16 v[50:65], v[138:141], v[178:181], v[50:65]
	ds_read_b64_tr_b16 v[178:179], v182 offset:0x2400
	ds_read_b64_tr_b16 v[180:181], v182 offset:0x2c00
	s_waitcnt lgkmcnt(6)
	v_mfma_f32_32x32x16_bf16 v[50:65], v[142:145], v[192:195], v[50:65]
	ds_read_b64_tr_b16 v[192:193], v182 offset:0x3400
	ds_read_b64_tr_b16 v[194:195], v182 offset:0x3c00
	s_waitcnt lgkmcnt(6)
	v_mfma_f32_32x32x16_bf16 v[34:49], v[130:133], v[170:173], v[34:49]
	ds_read_b64_tr_b16 v[170:171], v182 offset:0x600
	ds_read_b64_tr_b16 v[172:173], v182 offset:0xe00
	s_waitcnt lgkmcnt(6)
	v_mfma_f32_32x32x16_bf16 v[34:49], v[134:137], v[174:177], v[34:49]
	ds_read_b64_tr_b16 v[174:175], v182 offset:0x1600
	ds_read_b64_tr_b16 v[176:177], v182 offset:0x1e00
	s_waitcnt lgkmcnt(6)
	v_mfma_f32_32x32x16_bf16 v[34:49], v[138:141], v[178:181], v[34:49]
	ds_read_b64_tr_b16 v[178:179], v182 offset:0x2600
	ds_read_b64_tr_b16 v[180:181], v182 offset:0x2e00
	s_waitcnt lgkmcnt(6)
	v_mfma_f32_32x32x16_bf16 v[34:49], v[142:145], v[192:195], v[34:49]
	ds_read_b64_tr_b16 v[192:193], v182 offset:0x3600
	ds_read_b64_tr_b16 v[194:195], v182 offset:0x3e00
	s_waitcnt lgkmcnt(6)
	v_mfma_f32_32x32x16_bf16 v[18:33], v[130:133], v[170:173], v[18:33]
	v_max_f32_e32 v130, v83, v83
	v_max_f32_e32 v131, v82, v82
	v_max_f32_e32 v130, v131, v130
	v_max3_f32 v130, v130, v84, v85
	v_max3_f32 v130, v130, v86, v87
	v_max3_f32 v130, v130, v88, v89
	v_max3_f32 v130, v130, v90, v91
	v_max3_f32 v130, v130, v92, v93
	v_max3_f32 v130, v130, v94, v95
	s_waitcnt lgkmcnt(4)
	v_mfma_f32_32x32x16_bf16 v[18:33], v[134:137], v[174:177], v[18:33]
	v_max3_f32 v130, v130, v96, v97
	v_max3_f32 v130, v130, v66, v67
	v_max3_f32 v130, v130, v68, v69
	v_max3_f32 v130, v130, v70, v71
	v_max3_f32 v130, v130, v72, v73
	v_max3_f32 v130, v130, v74, v75
	v_max3_f32 v130, v130, v76, v77
	v_max3_f32 v130, v130, v78, v79
	s_waitcnt lgkmcnt(2)
	v_mfma_f32_32x32x16_bf16 v[18:33], v[138:141], v[178:181], v[18:33]
	v_max3_f32 v130, v130, v80, v81
	v_mov_b32_e32 v131, v130
	s_nop 1
	v_permlane32_swap_b32_e32 v130, v131
	v_max_f32_e32 v131, v131, v131
	v_max_f32_e32 v130, v130, v130
	v_max_f32_e32 v130, v130, v131
	v_sub_f32_e32 v131, v130, v167
	v_cmp_ge_f32_e32 vcc, s33, v131
	v_max_f32_e32 v131, v167, v167
	v_max_f32_e32 v130, v131, v130
	s_waitcnt lgkmcnt(0)
	v_mfma_f32_32x32x16_bf16 v[18:33], v[142:145], v[192:195], v[18:33]
	v_sub_f32_e32 v131, v167, v130
	v_mul_f32_e32 v131, 0x3e0293ee, v131
	v_exp_f32_e32 v131, v131
	s_cmp_eq_u64 vcc, exec
	s_cselect_b64 s[40:41], -1, 0
	s_waitcnt lgkmcnt(0)
	s_barrier
	v_cndmask_b32_e64 v171, v131, 1.0, s[40:41]
	v_cmp_gt_f32_e32 vcc, 1.0, v171
	s_cbranch_vccz .LBB0_290
	s_and_saveexec_b64 s[6:7], s[38:39]
	ds_write_b32 v155, v171 offset:128
	s_or_b64 exec, exec, s[6:7]
	s_waitcnt lgkmcnt(0)
	v_add_u32_e32 v131, v153, v146
	ds_read_b128 v[132:135], v131 offset:224
	ds_read_b128 v[136:139], v131 offset:192
	ds_read_b128 v[140:143], v131 offset:160
	ds_read_b128 v[172:175], v131 offset:128
	s_waitcnt lgkmcnt(3)
	v_pk_mul_f32 v[14:15], v[14:15], v[132:133]
	s_waitcnt lgkmcnt(2)
	v_pk_mul_f32 v[10:11], v[10:11], v[136:137]
	s_waitcnt lgkmcnt(1)
	v_pk_mul_f32 v[6:7], v[6:7], v[140:141]
	v_pk_mul_f32 v[16:17], v[16:17], v[134:135]
	v_pk_mul_f32 v[12:13], v[12:13], v[138:139]
	v_pk_mul_f32 v[8:9], v[8:9], v[142:143]
	s_waitcnt lgkmcnt(0)
	v_pk_mul_f32 v[4:5], v[4:5], v[174:175]
	v_pk_mul_f32 v[2:3], v[2:3], v[172:173]
	v_pk_mul_f32 v[62:63], v[62:63], v[132:133]
	v_pk_mul_f32 v[58:59], v[58:59], v[136:137]
	v_pk_mul_f32 v[54:55], v[54:55], v[140:141]
	v_pk_mul_f32 v[64:65], v[64:65], v[134:135]
	v_pk_mul_f32 v[60:61], v[60:61], v[138:139]
	v_pk_mul_f32 v[56:57], v[56:57], v[142:143]
	v_pk_mul_f32 v[52:53], v[52:53], v[174:175]
	v_pk_mul_f32 v[50:51], v[50:51], v[172:173]
	v_pk_mul_f32 v[46:47], v[46:47], v[132:133]
	v_pk_mul_f32 v[42:43], v[42:43], v[136:137]
	v_pk_mul_f32 v[38:39], v[38:39], v[140:141]
	v_pk_mul_f32 v[48:49], v[48:49], v[134:135]
	v_pk_mul_f32 v[44:45], v[44:45], v[138:139]
	v_pk_mul_f32 v[40:41], v[40:41], v[142:143]
	v_pk_mul_f32 v[36:37], v[36:37], v[174:175]
	v_pk_mul_f32 v[34:35], v[34:35], v[172:173]
	v_pk_mul_f32 v[30:31], v[30:31], v[132:133]
	v_pk_mul_f32 v[26:27], v[26:27], v[136:137]
	v_pk_mul_f32 v[22:23], v[22:23], v[140:141]
	v_pk_mul_f32 v[32:33], v[32:33], v[134:135]
	v_pk_mul_f32 v[28:29], v[28:29], v[138:139]
	v_pk_mul_f32 v[24:25], v[24:25], v[142:143]
	v_pk_mul_f32 v[20:21], v[20:21], v[174:175]
	v_pk_mul_f32 v[18:19], v[18:19], v[172:173]
; template <int DQK> __device__ __forceinline__ void partialSM(f32x16& p0, f32x16& p1, float& m_reg, float& mn, float& alpha) {
;     ...
;   else { mn = fmaxf(m_reg, pmax); alpha = __builtin_amdgcn_exp2f((m_reg - mn) * C); m_reg = mn; }
;   float mnC = -mn * C;
; #pragma unroll
;   for (int r = 0; r < 16; ++r) p0[r] = fmaf(p0[r], C, mnC);
; #pragma unroll
;   for (int r = 0; r < 16; ++r) p1[r] = fmaf(p1[r], C, mnC);
; #pragma unroll
;   for (int r = 0; r < 16; ++r) p0[r] = __builtin_amdgcn_exp2f(p0[r]);
; __device__ __forceinline__ void finishSM(f32x16& p0, f32x16& p1, float alpha, float& l_reg, bf16x8& pa0, bf16x8& pa1, bf16x8& pa2, bf16x8& pa3) {
; #pragma unroll
;   for (int r = 0; r < 16; ++r) p1[r] = __builtin_amdgcn_exp2f(p1[r]);
;   float ps = 0;
; #pragma unroll
;   for (int r = 0; r < 16; ++r) ps += p0[r];
; #pragma unroll
;   for (int r = 0; r < 16; ++r) ps += p1[r];
;   { auto rr = __builtin_amdgcn_permlane32_swap(__float_as_uint(ps), __float_as_uint(ps), false, false);
;     ps = __uint_as_float(rr[0]) + __uint_as_float(rr[1]); }
;   l_reg = l_reg * alpha + ps;
;     ...
;   PK4(p0, 0, pa0); PK4(p0, 8, pa1); PK4(p1, 0, pa2); PK4(p1, 8, pa3);
;     ...
; }
; template <int DQK, int KW, int QSP> __device__ __forceinline__ void qkt(f32x16& p0, f32x16& p1, const char* Ks, const int (&kb)[4], const bf16x8* qr, const char* qsp, const f32x16& cinit) {
;   p0 = cinit; p1 = cinit;
;   constexpr int N = DQK / 16;
;     ...
;   bf16x8 f0[2], f1[2];
;   f0[0] = KRD(0, 1); f1[0] = KRD(0, 0);
; #pragma unroll
;   for (int d0 = 0; d0 < N; ++d0) {
;     if (d0 + 1 < N) { f0[(d0 + 1) & 1] = KRD(d0 + 1, 1); f1[(d0 + 1) & 1] = KRD(d0 + 1, 0); }
;     __builtin_amdgcn_sched_barrier(0x406);
;     bf16x8 qf;
;     if constexpr (QSP > 0) { if (d0 >= N - QSP) qf = *reinterpret_cast<const bf16x8*>(qsp + (d0 - (N - QSP)) * 1024); else qf = qr[d0]; } else qf = qr[d0];
;     p0 = __builtin_amdgcn_mfma_f32_32x32x16_bf16(f0[d0 & 1], qf, p0, 0, 0, 0);
;     p1 = __builtin_amdgcn_mfma_f32_32x32x16_bf16(f1[d0 & 1], qf, p1, 0, 0, 0);
;     __builtin_amdgcn_sched_barrier(0x406); }
;     ...
; }
.LBB0_290:
	v_cndmask_b32_e64 v167, v130, v167, s[40:41]
	s_add_i32 s6, s27, 1
	v_mul_f32_e32 v170, 0xbe0293ee, v167
	s_cmp_lg_u32 s27, 2
	v_fmamk_f32 v82, v82, 0x3e0293ee, v170
	v_fmamk_f32 v83, v83, 0x3e0293ee, v170
	v_fmamk_f32 v84, v84, 0x3e0293ee, v170
	v_fmamk_f32 v85, v85, 0x3e0293ee, v170
	v_fmamk_f32 v86, v86, 0x3e0293ee, v170
	v_fmamk_f32 v87, v87, 0x3e0293ee, v170
	v_fmamk_f32 v88, v88, 0x3e0293ee, v170
	v_fmamk_f32 v89, v89, 0x3e0293ee, v170
	v_fmamk_f32 v90, v90, 0x3e0293ee, v170
	v_fmamk_f32 v91, v91, 0x3e0293ee, v170
	v_fmamk_f32 v92, v92, 0x3e0293ee, v170
	v_fmamk_f32 v93, v93, 0x3e0293ee, v170
	v_fmamk_f32 v94, v94, 0x3e0293ee, v170
	v_fmamk_f32 v95, v95, 0x3e0293ee, v170
	v_fmamk_f32 v96, v96, 0x3e0293ee, v170
	v_fmamk_f32 v97, v97, 0x3e0293ee, v170
	v_fmamk_f32 v196, v78, 0x3e0293ee, v170
	v_fmamk_f32 v197, v79, 0x3e0293ee, v170
	s_cselect_b32 s30, s6, 0
	v_fmamk_f32 v176, v66, 0x3e0293ee, v170
	v_fmamk_f32 v177, v67, 0x3e0293ee, v170
	v_fmamk_f32 v178, v68, 0x3e0293ee, v170
	v_fmamk_f32 v179, v69, 0x3e0293ee, v170
	v_fmamk_f32 v180, v70, 0x3e0293ee, v170
	v_fmamk_f32 v181, v71, 0x3e0293ee, v170
	v_fmamk_f32 v182, v72, 0x3e0293ee, v170
	v_fmamk_f32 v183, v73, 0x3e0293ee, v170
	v_fmamk_f32 v192, v74, 0x3e0293ee, v170
	v_fmamk_f32 v193, v75, 0x3e0293ee, v170
	v_fmamk_f32 v194, v76, 0x3e0293ee, v170
	v_fmamk_f32 v195, v77, 0x3e0293ee, v170
	v_fmamk_f32 v198, v80, 0x3e0293ee, v170
	v_fmac_f32_e32 v170, 0x3e0293ee, v81
	v_exp_f32_e32 v199, v82
	v_exp_f32_e32 v200, v83
	v_exp_f32_e32 v201, v84
	v_exp_f32_e32 v202, v85
	v_exp_f32_e32 v203, v86
	v_exp_f32_e32 v204, v87
	v_exp_f32_e32 v205, v88
	v_exp_f32_e32 v206, v89
	v_exp_f32_e32 v207, v90
	v_exp_f32_e32 v208, v91
	v_exp_f32_e32 v209, v92
	v_exp_f32_e32 v210, v93
	v_exp_f32_e32 v211, v94
	v_exp_f32_e32 v212, v95
	v_exp_f32_e32 v213, v96
	v_exp_f32_e32 v214, v97
	v_add_u32_e32 v172, s9, v163
	v_add_u32_e32 v173, s9, v158
	ds_read_b128 v[130:133], v172 offset:49152
	ds_read_b128 v[134:137], v172 offset:57344
	ds_read_b128 v[66:69], v173 offset:57344
	ds_read_b128 v[70:73], v173 offset:49152
	v_add_u32_e32 v215, s9, v164
	v_add_u32_e32 v216, s9, v165
	s_waitcnt lgkmcnt(0)
	v_mfma_f32_32x32x16_bf16 v[82:97], v[70:73], v[102:105], 0
	v_exp_f32_e32 v170, v170
	v_mfma_f32_32x32x16_bf16 v[66:81], v[66:69], v[102:105], 0
	ds_read_b128 v[138:141], v215 offset:49152
	ds_read_b128 v[142:145], v215 offset:57344
	v_mfma_f32_32x32x16_bf16 v[82:97], v[130:133], v[110:113], v[82:97]
	v_mfma_f32_32x32x16_bf16 v[66:81], v[134:137], v[110:113], v[66:81]
	ds_read_b128 v[130:133], v216 offset:49152
	ds_read_b128 v[134:137], v216 offset:57344
	s_waitcnt lgkmcnt(3)
	v_mfma_f32_32x32x16_bf16 v[82:97], v[138:141], v[106:109], v[82:97]
	s_waitcnt lgkmcnt(2)
	v_mfma_f32_32x32x16_bf16 v[66:81], v[142:145], v[106:109], v[66:81]
	ds_read_b128 v[138:141], v173 offset:49280
	ds_read_b128 v[142:145], v173 offset:57472
	s_waitcnt lgkmcnt(3)
	v_mfma_f32_32x32x16_bf16 v[82:97], v[130:133], v[98:101], v[82:97]
	s_waitcnt lgkmcnt(2)
	v_mfma_f32_32x32x16_bf16 v[66:81], v[134:137], v[98:101], v[66:81]
	ds_read_b128 v[130:133], v172 offset:49280
	ds_read_b128 v[134:137], v172 offset:57472
	s_waitcnt lgkmcnt(3)
	v_mfma_f32_32x32x16_bf16 v[82:97], v[138:141], v[220:223], v[82:97]
	s_waitcnt lgkmcnt(2)
	v_mfma_f32_32x32x16_bf16 v[66:81], v[142:145], v[220:223], v[66:81]
	ds_read_b128 v[138:141], v215 offset:49280
	ds_read_b128 v[142:145], v215 offset:57472
	s_waitcnt lgkmcnt(3)
	v_mfma_f32_32x32x16_bf16 v[82:97], v[130:133], v[224:227], v[82:97]
	s_waitcnt lgkmcnt(2)
	v_mfma_f32_32x32x16_bf16 v[66:81], v[134:137], v[224:227], v[66:81]
	ds_read_b128 v[130:133], v216 offset:49280
	ds_read_b128 v[134:137], v216 offset:57472
	s_waitcnt lgkmcnt(3)
	v_mfma_f32_32x32x16_bf16 v[82:97], v[138:141], v[228:231], v[82:97]
	s_waitcnt lgkmcnt(2)
	v_mfma_f32_32x32x16_bf16 v[66:81], v[142:145], v[228:231], v[66:81]
	v_exp_f32_e32 v142, v180
	v_exp_f32_e32 v143, v181
	v_exp_f32_e32 v144, v182
	v_exp_f32_e32 v145, v183
	v_exp_f32_e32 v172, v192
	v_exp_f32_e32 v173, v193
	s_waitcnt lgkmcnt(0)
	v_mfma_f32_32x32x16_bf16 v[82:97], v[130:133], v[232:235], v[82:97]
	v_add_f32_e32 v130, 0, v199
	v_add_f32_e32 v252, 0, v200
	v_add_f32_e32 v130, v201, v130
	v_add_f32_e32 v252, v202, v252
	v_add_f32_e32 v130, v203, v130
	v_add_f32_e32 v252, v204, v252
	v_add_f32_e32 v130, v205, v130
	v_add_f32_e32 v252, v206, v252
	v_add_f32_e32 v130, v207, v130
	v_add_f32_e32 v252, v208, v252
	v_add_f32_e32 v130, v209, v130
	v_add_f32_e32 v252, v210, v252
	v_mfma_f32_32x32x16_bf16 v[66:81], v[134:137], v[232:235], v[66:81]
	v_exp_f32_e32 v138, v176
	v_add_f32_e32 v130, v211, v130
	v_exp_f32_e32 v139, v177
	v_add_f32_e32 v252, v212, v252
	v_exp_f32_e32 v140, v178
	v_add_f32_e32 v130, v213, v130
	v_exp_f32_e32 v141, v179
	v_add_f32_e32 v252, v214, v252
	v_add_f32_e32 v130, v138, v130
	v_add_f32_e32 v252, v139, v252
	v_add_f32_e32 v130, v140, v130
	v_add_f32_e32 v252, v141, v252
	v_add_f32_e32 v130, v142, v130
	v_add_f32_e32 v252, v143, v252
	v_exp_f32_e32 v174, v194
	v_add_f32_e32 v130, v144, v130
	v_exp_f32_e32 v175, v195
	v_add_f32_e32 v252, v145, v252
	v_exp_f32_e32 v176, v196
	v_add_f32_e32 v130, v172, v130
	v_exp_f32_e32 v177, v197
	v_add_f32_e32 v252, v173, v252
	v_exp_f32_e32 v178, v198
	v_add_f32_e32 v130, v174, v130
	v_add_f32_e32 v252, v175, v252
	v_add_f32_e32 v130, v176, v130
	v_add_f32_e32 v252, v177, v252
	v_add_f32_e32 v130, v178, v130
	v_add_f32_e32 v130, v252, v130
	v_add_f32_e32 v196, v170, v130
	v_mov_b32_e32 v197, v196
	v_cvt_pk_bf16_f32 v130, v199, v200
	v_cvt_pk_bf16_f32 v131, v201, v202
	v_cvt_pk_bf16_f32 v132, v203, v204
	v_cvt_pk_bf16_f32 v133, v205, v206
	v_cvt_pk_bf16_f32 v134, v207, v208
	v_cvt_pk_bf16_f32 v135, v209, v210
	v_cvt_pk_bf16_f32 v136, v211, v212
	v_cvt_pk_bf16_f32 v137, v213, v214
	v_cvt_pk_bf16_f32 v138, v138, v139
	v_cvt_pk_bf16_f32 v139, v140, v141
	v_cvt_pk_bf16_f32 v140, v142, v143
	v_cvt_pk_bf16_f32 v141, v144, v145
	v_cvt_pk_bf16_f32 v142, v172, v173
	v_cvt_pk_bf16_f32 v143, v174, v175
	v_cvt_pk_bf16_f32 v144, v176, v177
	v_cvt_pk_bf16_f32 v145, v178, v170
	s_nop 1
	v_permlane32_swap_b32_e32 v196, v197
	v_permlane32_swap_b32_e32 v130, v132
	v_permlane32_swap_b32_e32 v131, v133
	v_permlane32_swap_b32_e32 v134, v136
	v_permlane32_swap_b32_e32 v135, v137
	v_permlane32_swap_b32_e32 v138, v140
	v_permlane32_swap_b32_e32 v139, v141
	v_permlane32_swap_b32_e32 v142, v144
	v_permlane32_swap_b32_e32 v143, v145
	s_lshl_b32 s29, s30, 14
	s_add_i32 s31, s29, 0
	s_waitcnt vmcnt(0)
	v_add_u32_e32 v170, s31, v159
	s_cmp_ge_u32 s25, s26
	s_waitcnt vmcnt(3)
	ds_write_b128 v170, v[114:117]
	v_add_u32_e32 v170, s31, v160
	s_cselect_b64 s[6:7], -1, 0
	s_waitcnt vmcnt(2)
	ds_write_b128 v170, v[118:121]
	v_add_u32_e32 v170, s29, v162
	s_and_b64 vcc, exec, s[6:7]
	s_waitcnt vmcnt(1)
	ds_write_b128 v170, v[122:125] offset:49152
	s_waitcnt vmcnt(0)
	ds_write_b128 v170, v[126:129] offset:57344
	s_cbranch_vccnz .LBB0_292
	v_add_co_u32_e32 v114, vcc, 0xffff8000, v148
	s_nop 1
	v_addc_co_u32_e32 v115, vcc, -1, v149, vcc
	v_add_co_u32_e32 v118, vcc, 0xfb7f8000, v148
	s_nop 1
	v_addc_co_u32_e32 v119, vcc, -1, v149, vcc
	v_add_co_u32_e32 v126, vcc, 0xfb800000, v148
	global_load_dwordx4 v[114:117], v[114:115], off
	s_nop 0
	global_load_dwordx4 v[122:125], v[118:119], off
	v_addc_co_u32_e32 v127, vcc, -1, v149, vcc
	global_load_dwordx4 v[118:121], v[148:149], off
	s_nop 0
	global_load_dwordx4 v[126:129], v[126:127], off

; __device__ __forceinline__ void finishSM(f32x16& p0, f32x16& p1, float alpha, float& l_reg, bf16x8& pa0, bf16x8& pa1, bf16x8& pa2, bf16x8& pa3) {
; #pragma unroll
;   for (int r = 0; r < 16; ++r) p1[r] = __builtin_amdgcn_exp2f(p1[r]);
;   float ps = 0;
; #pragma unroll
;   for (int r = 0; r < 16; ++r) ps += p0[r];
; #pragma unroll
;   for (int r = 0; r < 16; ++r) ps += p1[r];
;   { auto rr = __builtin_amdgcn_permlane32_swap(__float_as_uint(ps), __float_as_uint(ps), false, false);
;     ps = __uint_as_float(rr[0]) + __uint_as_float(rr[1]); }
;   l_reg = l_reg * alpha + ps;
;     ...
;   PK4(p0, 0, pa0); PK4(p0, 8, pa1); PK4(p1, 0, pa2); PK4(p1, 8, pa3);
;     ...
; }
; template <int DQK, int KW, int QSP> __device__ __forceinline__ void qkt(f32x16& p0, f32x16& p1, const char* Ks, const int (&kb)[4], const bf16x8* qr, const char* qsp, const f32x16& cinit) {
;   p0 = cinit; p1 = cinit;
;   constexpr int N = DQK / 16;
;     ...
;   bf16x8 f0[2], f1[2];
;   f0[0] = KRD(0, 1); f1[0] = KRD(0, 0);
; #pragma unroll
;   for (int d0 = 0; d0 < N; ++d0) {
;     if (d0 + 1 < N) { f0[(d0 + 1) & 1] = KRD(d0 + 1, 1); f1[(d0 + 1) & 1] = KRD(d0 + 1, 0); }
;     __builtin_amdgcn_sched_barrier(0x406);
;     bf16x8 qf;
;     if constexpr (QSP > 0) { if (d0 >= N - QSP) qf = *reinterpret_cast<const bf16x8*>(qsp + (d0 - (N - QSP)) * 1024); else qf = qr[d0]; } else qf = qr[d0];
;     p0 = __builtin_amdgcn_mfma_f32_32x32x16_bf16(f0[d0 & 1], qf, p0, 0, 0, 0);
;     p1 = __builtin_amdgcn_mfma_f32_32x32x16_bf16(f1[d0 & 1], qf, p1, 0, 0, 0);
;     __builtin_amdgcn_sched_barrier(0x406); }
;     ...
; }
.LBB0_316:
	s_lshl_b32 s10, s35, 14
	s_add_i32 s8, s10, 0
	v_add_u32_e32 v102, s8, v183
	ds_read_b128 v[98:101], v102 offset:49152
	v_add_u32_e32 v103, s8, v197
	ds_read_b128 v[200:203], v102 offset:57344
	ds_read_b128 v[222:225], v103 offset:49152
	ds_read_b128 v[226:229], v103 offset:57344
	v_add_u32_e32 v204, s8, v196
	v_exp_f32_e32 v205, v85
	v_exp_f32_e32 v97, v97
	s_waitcnt lgkmcnt(3)
	v_mfma_f32_32x32x16_bf16 v[114:129], v[98:101], v[142:145], v[66:81]
	s_waitcnt lgkmcnt(2)
	v_mfma_f32_32x32x16_bf16 v[98:113], v[200:203], v[142:145], v[66:81]
	ds_read_b128 v[200:203], v204 offset:49152
	ds_read_b128 v[230:233], v204 offset:57344
	v_add_u32_e32 v204, s8, v198
	s_waitcnt lgkmcnt(3)
	v_mfma_f32_32x32x16_bf16 v[114:129], v[222:225], v[138:141], v[114:129]
	s_waitcnt lgkmcnt(2)
	v_mfma_f32_32x32x16_bf16 v[98:113], v[226:229], v[138:141], v[98:113]
	ds_read_b128 v[222:225], v204 offset:49152
	ds_read_b128 v[226:229], v204 offset:57344
	v_exp_f32_e32 v204, v84
	s_waitcnt lgkmcnt(3)
	v_mfma_f32_32x32x16_bf16 v[114:129], v[200:203], v[134:137], v[114:129]
	v_exp_f32_e32 v202, v82
	v_add_f32_e32 v82, 0, v219
	v_add_f32_e32 v252, 0, v221
	v_add_f32_e32 v82, v217, v82
	v_add_f32_e32 v252, v220, v252
	v_add_f32_e32 v82, v215, v82
	v_add_f32_e32 v252, v218, v252
	v_add_f32_e32 v82, v214, v82
	v_add_f32_e32 v252, v216, v252
	v_add_f32_e32 v82, v211, v82
	v_add_f32_e32 v252, v213, v252
	v_add_f32_e32 v82, v209, v82
	v_add_f32_e32 v252, v212, v252
	s_waitcnt lgkmcnt(2)
	v_mfma_f32_32x32x16_bf16 v[98:113], v[230:233], v[134:137], v[98:113]
	v_add_f32_e32 v82, v207, v82
	v_exp_f32_e32 v203, v83
	v_add_f32_e32 v252, v210, v252
	v_add_f32_e32 v82, v206, v82
	v_add_f32_e32 v252, v208, v252
	v_add_f32_e32 v82, v202, v82
	v_add_f32_e32 v252, v203, v252
	s_waitcnt lgkmcnt(1)
	v_mfma_f32_32x32x16_bf16 v[114:129], v[222:225], v[130:133], v[114:129]
	v_exp_f32_e32 v222, v86
	v_exp_f32_e32 v223, v87
	v_exp_f32_e32 v224, v88
	v_add_f32_e32 v82, v204, v82
	v_exp_f32_e32 v225, v89
	v_add_f32_e32 v252, v205, v252
	v_add_f32_e32 v82, v222, v82
	s_waitcnt lgkmcnt(0)
	v_mfma_f32_32x32x16_bf16 v[98:113], v[226:229], v[130:133], v[98:113]
	v_exp_f32_e32 v226, v90
	v_exp_f32_e32 v227, v91
	v_add_f32_e32 v252, v223, v252
	v_exp_f32_e32 v228, v92
	v_add_f32_e32 v82, v224, v82
	v_exp_f32_e32 v229, v93
	v_add_f32_e32 v252, v225, v252
	v_exp_f32_e32 v230, v94
	v_add_f32_e32 v82, v226, v82
	v_exp_f32_e32 v231, v95
	v_add_f32_e32 v252, v227, v252
	v_exp_f32_e32 v232, v96
	v_add_f32_e32 v82, v228, v82
	v_add_f32_e32 v252, v229, v252
	v_add_f32_e32 v82, v230, v82
	v_add_f32_e32 v252, v231, v252
	v_add_f32_e32 v82, v232, v82
	v_add_f32_e32 v82, v252, v82
	v_add_f32_e32 v200, v97, v82
	v_mov_b32_e32 v201, v200
	v_cvt_pk_bf16_f32 v82, v219, v221
	v_cvt_pk_bf16_f32 v83, v217, v220
	v_cvt_pk_bf16_f32 v84, v215, v218
	s_nop 1
	v_permlane32_swap_b32_e32 v200, v201
	v_cvt_pk_bf16_f32 v85, v214, v216
	v_permlane32_swap_b32_e32 v82, v84
	v_cvt_pk_bf16_f32 v86, v211, v213
	v_cvt_pk_bf16_f32 v87, v209, v212
	v_cvt_pk_bf16_f32 v88, v207, v210
	v_cvt_pk_bf16_f32 v89, v206, v208
	v_cvt_pk_bf16_f32 v90, v202, v203
	v_cvt_pk_bf16_f32 v91, v204, v205
	v_cvt_pk_bf16_f32 v92, v222, v223
	v_cvt_pk_bf16_f32 v93, v224, v225
	v_cvt_pk_bf16_f32 v94, v226, v227
	v_cvt_pk_bf16_f32 v95, v228, v229
	v_cvt_pk_bf16_f32 v96, v230, v231
	v_cvt_pk_bf16_f32 v97, v232, v97
	v_permlane32_swap_b32_e32 v83, v85
	v_permlane32_swap_b32_e32 v86, v88
	v_permlane32_swap_b32_e32 v87, v89
	v_permlane32_swap_b32_e32 v90, v92
	v_permlane32_swap_b32_e32 v91, v93
	v_permlane32_swap_b32_e32 v94, v96
	v_permlane32_swap_b32_e32 v95, v97
	s_lshl_b32 s13, s12, 14
	s_add_i32 s11, s13, 0
	v_add_u32_e32 v202, s11, v192
	s_waitcnt vmcnt(0)
	s_waitcnt vmcnt(3)
	ds_write_b128 v202, v[146:149]
	v_add_u32_e32 v146, s11, v193
	s_waitcnt vmcnt(1)
	ds_write_b128 v146, v[150:153]
	v_add_u32_e32 v146, s11, v194
	s_mov_b32 s8, 0xfffa0000
	s_waitcnt vmcnt(1)
	ds_write_b128 v146, v[154:157] offset:49152
	s_waitcnt vmcnt(0)
; #define SBAR() __builtin_amdgcn_sched_barrier(0)
; template <int D0> __device__ __forceinline__ void pv_one(f32x16& od, int vb, bf16x8 pa0, bf16x8 pa1, bf16x8 pa2, bf16x8 pa3) {
;   const s16x4 l0 = tr_read<v_rd_off(D0, 0, 0)>(vb), h0 = tr_read<v_rd_off(D0, 0, 1)>(vb), l1 = tr_read<v_rd_off(D0, 1, 0)>(vb), h1 = tr_read<v_rd_off(D0, 1, 1)>(vb);
;   const s16x4 l2 = tr_read<v_rd_off(D0, 2, 0)>(vb), h2 = tr_read<v_rd_off(D0, 2, 1)>(vb), l3 = tr_read<v_rd_off(D0, 3, 0)>(vb), h3 = tr_read<v_rd_off(D0, 3, 1)>(vb);
;   asm volatile("s_waitcnt lgkmcnt(0)" ::: "memory"); SBAR();
;     ...
;   od = __builtin_amdgcn_mfma_f32_32x32x16_bf16(pa0, PK(l0, h0), od, 0, 0, 0);
;   od = __builtin_amdgcn_mfma_f32_32x32x16_bf16(pa1, PK(l1, h1), od, 0, 0, 0);
;   od = __builtin_amdgcn_mfma_f32_32x32x16_bf16(pa2, PK(l2, h2), od, 0, 0, 0);
;   od = __builtin_amdgcn_mfma_f32_32x32x16_bf16(pa3, PK(l3, h3), od, 0, 0, 0);
;     ...
; }
	ds_write_b128 v146, v[158:161] offset:57344
	v_add_co_u32_e32 v146, vcc, s8, v166
	s_mov_b32 s8, 0xfffc0000
	s_nop 0
	v_addc_co_u32_e32 v147, vcc, -1, v167, vcc
	v_add_co_u32_e32 v150, vcc, s8, v166
	s_mov_b32 s8, 0xfb7a0000
	s_nop 0
	v_addc_co_u32_e32 v151, vcc, -1, v167, vcc
	v_add_co_u32_e32 v154, vcc, s8, v166
	s_mov_b32 s8, 0xfb7c0000
	s_nop 0
	v_addc_co_u32_e32 v155, vcc, -1, v167, vcc
	v_add_co_u32_e32 v158, vcc, s8, v166
	global_load_dwordx4 v[146:149], v[146:147], off
	s_nop 0
	global_load_dwordx4 v[150:153], v[150:151], off
	v_addc_co_u32_e32 v159, vcc, -1, v167, vcc
	global_load_dwordx4 v[154:157], v[154:155], off
	s_nop 0
	global_load_dwordx4 v[158:161], v[158:159], off
	v_lshl_add_u32 v218, s9, 14, v181
	ds_read_b64_tr_b16 v[202:203], v218 offset:0
	ds_read_b64_tr_b16 v[204:205], v218 offset:0x800
	ds_read_b64_tr_b16 v[206:207], v218 offset:0x1000
	ds_read_b64_tr_b16 v[208:209], v218 offset:0x1800
	ds_read_b64_tr_b16 v[210:211], v218 offset:0x2000
	ds_read_b64_tr_b16 v[212:213], v218 offset:0x2800
	ds_read_b64_tr_b16 v[214:215], v218 offset:0x3000
	ds_read_b64_tr_b16 v[216:217], v218 offset:0x3800
	s_waitcnt lgkmcnt(6)
	s_nop 0
	v_mfma_f32_32x32x16_bf16 v[2:17], v[82:85], v[202:205], v[2:17]
	ds_read_b64_tr_b16 v[202:203], v218 offset:0x200
	ds_read_b64_tr_b16 v[204:205], v218 offset:0xa00
	s_waitcnt lgkmcnt(6)
	v_mfma_f32_32x32x16_bf16 v[2:17], v[86:89], v[206:209], v[2:17]
	ds_read_b64_tr_b16 v[206:207], v218 offset:0x1200
	ds_read_b64_tr_b16 v[208:209], v218 offset:0x1a00
	s_waitcnt lgkmcnt(6)
	v_mfma_f32_32x32x16_bf16 v[2:17], v[90:93], v[210:213], v[2:17]
	ds_read_b64_tr_b16 v[210:211], v218 offset:0x2200
	ds_read_b64_tr_b16 v[212:213], v218 offset:0x2a00
	s_waitcnt lgkmcnt(6)
	v_mfma_f32_32x32x16_bf16 v[2:17], v[94:97], v[214:217], v[2:17]
	ds_read_b64_tr_b16 v[214:215], v218 offset:0x3200
	ds_read_b64_tr_b16 v[216:217], v218 offset:0x3a00
	s_waitcnt lgkmcnt(6)
	v_mfma_f32_32x32x16_bf16 v[50:65], v[82:85], v[202:205], v[50:65]
	ds_read_b64_tr_b16 v[202:203], v218 offset:0x400
	ds_read_b64_tr_b16 v[204:205], v218 offset:0xc00
	s_waitcnt lgkmcnt(6)
	v_mfma_f32_32x32x16_bf16 v[50:65], v[86:89], v[206:209], v[50:65]
	ds_read_b64_tr_b16 v[206:207], v218 offset:0x1400
	ds_read_b64_tr_b16 v[208:209], v218 offset:0x1c00
	s_waitcnt lgkmcnt(6)
	v_mfma_f32_32x32x16_bf16 v[50:65], v[90:93], v[210:213], v[50:65]
	ds_read_b64_tr_b16 v[210:211], v218 offset:0x2400
	ds_read_b64_tr_b16 v[212:213], v218 offset:0x2c00
	s_waitcnt lgkmcnt(6)
	v_mfma_f32_32x32x16_bf16 v[50:65], v[94:97], v[214:217], v[50:65]
	ds_read_b64_tr_b16 v[214:215], v218 offset:0x3400
	ds_read_b64_tr_b16 v[216:217], v218 offset:0x3c00
	s_waitcnt lgkmcnt(6)
	v_mfma_f32_32x32x16_bf16 v[34:49], v[82:85], v[202:205], v[34:49]
	ds_read_b64_tr_b16 v[202:203], v218 offset:0x600
	ds_read_b64_tr_b16 v[204:205], v218 offset:0xe00
	s_waitcnt lgkmcnt(6)
	v_mfma_f32_32x32x16_bf16 v[34:49], v[86:89], v[206:209], v[34:49]
	ds_read_b64_tr_b16 v[206:207], v218 offset:0x1600
	ds_read_b64_tr_b16 v[208:209], v218 offset:0x1e00
	s_waitcnt lgkmcnt(6)
	v_mfma_f32_32x32x16_bf16 v[34:49], v[90:93], v[210:213], v[34:49]
	ds_read_b64_tr_b16 v[210:211], v218 offset:0x2600
	ds_read_b64_tr_b16 v[212:213], v218 offset:0x2e00
	s_waitcnt lgkmcnt(6)
	v_mfma_f32_32x32x16_bf16 v[34:49], v[94:97], v[214:217], v[34:49]
	ds_read_b64_tr_b16 v[214:215], v218 offset:0x3600
	ds_read_b64_tr_b16 v[216:217], v218 offset:0x3e00
	s_waitcnt lgkmcnt(6)
	v_mfma_f32_32x32x16_bf16 v[18:33], v[82:85], v[202:205], v[18:33]
	v_max_f32_e32 v82, v115, v115
	v_max_f32_e32 v83, v114, v114
	v_max_f32_e32 v82, v83, v82
	v_max3_f32 v82, v82, v116, v117
	v_max3_f32 v82, v82, v118, v119
	v_max3_f32 v82, v82, v120, v121
	v_max3_f32 v82, v82, v122, v123
	s_waitcnt lgkmcnt(4)
	v_mfma_f32_32x32x16_bf16 v[18:33], v[86:89], v[206:209], v[18:33]
	v_max3_f32 v82, v82, v124, v125
	v_max3_f32 v82, v82, v126, v127
	v_max3_f32 v82, v82, v128, v129
	v_max3_f32 v82, v82, v98, v99
	v_max3_f32 v82, v82, v100, v101
	v_max3_f32 v82, v82, v102, v103
	v_max3_f32 v82, v82, v104, v105
	s_waitcnt lgkmcnt(2)
	v_mfma_f32_32x32x16_bf16 v[18:33], v[90:93], v[210:213], v[18:33]
	v_max3_f32 v82, v82, v106, v107
	v_max3_f32 v82, v82, v108, v109
	v_max3_f32 v82, v82, v110, v111
	v_max3_f32 v82, v82, v112, v113
	v_mov_b32_e32 v83, v82
	s_nop 1
	v_permlane32_swap_b32_e32 v82, v83
	s_waitcnt lgkmcnt(0)
	v_mfma_f32_32x32x16_bf16 v[18:33], v[94:97], v[214:217], v[18:33]
	v_max_f32_e32 v83, v83, v83
	v_max_f32_e32 v82, v82, v82
	v_max_f32_e32 v82, v82, v83
	v_cmp_ge_f32_e32 vcc, s0, v82
	s_cmp_eq_u64 vcc, exec
	s_cbranch_scc0 .LBB0_331
	v_mov_b32_e32 v203, 1.0

; template <bool FIRST> __device__ __forceinline__ void partialSM_ps(f32x16& p0, f32x16& p1, float& m_reg, float& alpha, f32x16& negm) {
;     ...
; #pragma unroll
;   for (int r = 0; r < 16; ++r) p0[r] = __builtin_amdgcn_exp2f(p0[r]);
; }
; __device__ __forceinline__ void finishSM(f32x16& p0, f32x16& p1, float alpha, float& l_reg, bf16x8& pa0, bf16x8& pa1, bf16x8& pa2, bf16x8& pa3) {
; #pragma unroll
;   for (int r = 0; r < 16; ++r) p1[r] = __builtin_amdgcn_exp2f(p1[r]);
;   float ps = 0;
; #pragma unroll
;   for (int r = 0; r < 16; ++r) ps += p0[r];
; #pragma unroll
;   for (int r = 0; r < 16; ++r) ps += p1[r];
;   { auto rr = __builtin_amdgcn_permlane32_swap(__float_as_uint(ps), __float_as_uint(ps), false, false);
;     ps = __uint_as_float(rr[0]) + __uint_as_float(rr[1]); }
;   l_reg = l_reg * alpha + ps;
;     ...
;   PK4(p0, 0, pa0); PK4(p0, 8, pa1); PK4(p1, 0, pa2); PK4(p1, 8, pa3);
;     ...
; }
; template <int DQK, int KW, int QSP> __device__ __forceinline__ void qkt(f32x16& p0, f32x16& p1, const char* Ks, const int (&kb)[4], const bf16x8* qr, const char* qsp, const f32x16& cinit) {
;   p0 = cinit; p1 = cinit;
;   constexpr int N = DQK / 16;
;     ...
;   bf16x8 f0[2], f1[2];
;   f0[0] = KRD(0, 1); f1[0] = KRD(0, 0);
; #pragma unroll
;   for (int d0 = 0; d0 < N; ++d0) {
;     if (d0 + 1 < N) { f0[(d0 + 1) & 1] = KRD(d0 + 1, 1); f1[(d0 + 1) & 1] = KRD(d0 + 1, 0); }
;     __builtin_amdgcn_sched_barrier(0x406);
;     bf16x8 qf;
;     if constexpr (QSP > 0) { if (d0 >= N - QSP) qf = *reinterpret_cast<const bf16x8*>(qsp + (d0 - (N - QSP)) * 1024); else qf = qr[d0]; } else qf = qr[d0];
;     p0 = __builtin_amdgcn_mfma_f32_32x32x16_bf16(f0[d0 & 1], qf, p0, 0, 0, 0);
;     p1 = __builtin_amdgcn_mfma_f32_32x32x16_bf16(f1[d0 & 1], qf, p1, 0, 0, 0);
;     __builtin_amdgcn_sched_barrier(0x406); }
;     ...
; }
.LBB0_322:
	s_add_i32 s8, s12, 1
	s_cmp_lg_u32 s12, 2
	s_cselect_b32 s35, s8, 0
	v_exp_f32_e32 v202, v114
	v_exp_f32_e32 v220, v115
	v_exp_f32_e32 v221, v116
	v_exp_f32_e32 v222, v117
	v_exp_f32_e32 v223, v118
	v_exp_f32_e32 v224, v119
	v_exp_f32_e32 v225, v120
	v_exp_f32_e32 v226, v121
	v_exp_f32_e32 v227, v122
	v_exp_f32_e32 v228, v123
	v_exp_f32_e32 v229, v124
	v_exp_f32_e32 v230, v125
	v_exp_f32_e32 v231, v126
	v_exp_f32_e32 v232, v127
	v_exp_f32_e32 v233, v128
	v_exp_f32_e32 v234, v129
	v_add_u32_e32 v86, s11, v183
	ds_read_b128 v[82:85], v86 offset:49152
	v_add_u32_e32 v87, s11, v197
	ds_read_b128 v[204:207], v86 offset:57344
	ds_read_b128 v[208:211], v87 offset:49152
	ds_read_b128 v[212:215], v87 offset:57344
	v_add_u32_e32 v216, s11, v196
	v_exp_f32_e32 v235, v112
	v_exp_f32_e32 v113, v113
	s_waitcnt lgkmcnt(3)
	v_mfma_f32_32x32x16_bf16 v[114:129], v[82:85], v[142:145], v[66:81]
	s_waitcnt lgkmcnt(2)
	v_mfma_f32_32x32x16_bf16 v[82:97], v[204:207], v[142:145], v[66:81]
	ds_read_b128 v[204:207], v216 offset:49152
	ds_read_b128 v[216:219], v216 offset:57344
	s_waitcnt lgkmcnt(3)
	v_mfma_f32_32x32x16_bf16 v[114:129], v[208:211], v[138:141], v[114:129]
	s_waitcnt lgkmcnt(2)
	v_mfma_f32_32x32x16_bf16 v[82:97], v[212:215], v[138:141], v[82:97]
	v_add_u32_e32 v212, s11, v198
	ds_read_b128 v[208:211], v212 offset:49152
	ds_read_b128 v[212:215], v212 offset:57344
	s_waitcnt lgkmcnt(3)
	v_mfma_f32_32x32x16_bf16 v[114:129], v[204:207], v[134:137], v[114:129]
	v_exp_f32_e32 v206, v98
	v_add_f32_e32 v98, 0, v202
	v_add_f32_e32 v252, 0, v220
	v_add_f32_e32 v98, v221, v98
	v_add_f32_e32 v252, v222, v252
	v_add_f32_e32 v98, v223, v98
	v_add_f32_e32 v252, v224, v252
	v_add_f32_e32 v98, v225, v98
	v_add_f32_e32 v252, v226, v252
	v_add_f32_e32 v98, v227, v98
	v_add_f32_e32 v252, v228, v252
	s_waitcnt lgkmcnt(2)
	v_mfma_f32_32x32x16_bf16 v[82:97], v[216:219], v[134:137], v[82:97]
	v_add_f32_e32 v98, v229, v98
	v_add_f32_e32 v252, v230, v252
	v_add_f32_e32 v98, v231, v98
	v_exp_f32_e32 v207, v99
	v_add_f32_e32 v252, v232, v252
	v_add_f32_e32 v98, v233, v98
	v_add_f32_e32 v252, v234, v252
	s_waitcnt lgkmcnt(1)
	v_mfma_f32_32x32x16_bf16 v[114:129], v[208:211], v[130:133], v[114:129]
	v_exp_f32_e32 v208, v100
	v_exp_f32_e32 v209, v101
	v_exp_f32_e32 v210, v102
	v_add_f32_e32 v98, v206, v98
	v_exp_f32_e32 v211, v103
	v_add_f32_e32 v252, v207, v252
	v_add_f32_e32 v98, v208, v98
	s_waitcnt lgkmcnt(0)
	v_mfma_f32_32x32x16_bf16 v[82:97], v[212:215], v[130:133], v[82:97]
	v_exp_f32_e32 v212, v104
	v_exp_f32_e32 v213, v105
	v_add_f32_e32 v252, v209, v252
	v_exp_f32_e32 v214, v106
	v_add_f32_e32 v98, v210, v98
	v_exp_f32_e32 v215, v107
	v_add_f32_e32 v252, v211, v252
	v_exp_f32_e32 v216, v108
	v_add_f32_e32 v98, v212, v98
	v_exp_f32_e32 v217, v109
	v_add_f32_e32 v252, v213, v252
	v_exp_f32_e32 v218, v110
	v_add_f32_e32 v98, v214, v98
	v_exp_f32_e32 v219, v111
	v_add_f32_e32 v252, v215, v252
	v_add_f32_e32 v98, v216, v98
	v_add_f32_e32 v252, v217, v252
	v_add_f32_e32 v98, v218, v98
	v_add_f32_e32 v252, v219, v252
	v_add_f32_e32 v98, v235, v98
	v_add_f32_e32 v98, v252, v98
	v_add_f32_e32 v204, v113, v98
	v_mov_b32_e32 v205, v204
	v_cvt_pk_bf16_f32 v98, v202, v220
	v_cvt_pk_bf16_f32 v99, v221, v222
	v_cvt_pk_bf16_f32 v100, v223, v224
	v_cvt_pk_bf16_f32 v101, v225, v226
	v_cvt_pk_bf16_f32 v102, v227, v228
	v_cvt_pk_bf16_f32 v103, v229, v230
	v_cvt_pk_bf16_f32 v104, v231, v232
	v_cvt_pk_bf16_f32 v105, v233, v234
	v_cvt_pk_bf16_f32 v106, v206, v207
	v_cvt_pk_bf16_f32 v107, v208, v209
	v_cvt_pk_bf16_f32 v108, v210, v211
	v_cvt_pk_bf16_f32 v109, v212, v213
	v_cvt_pk_bf16_f32 v110, v214, v215
	v_cvt_pk_bf16_f32 v111, v216, v217
	v_cvt_pk_bf16_f32 v112, v218, v219
	v_cvt_pk_bf16_f32 v113, v235, v113
	s_nop 1
	v_permlane32_swap_b32_e32 v204, v205
	v_permlane32_swap_b32_e32 v98, v100
	v_permlane32_swap_b32_e32 v99, v101
	v_permlane32_swap_b32_e32 v102, v104
	v_permlane32_swap_b32_e32 v103, v105
	v_permlane32_swap_b32_e32 v106, v108
	v_permlane32_swap_b32_e32 v107, v109
	v_permlane32_swap_b32_e32 v110, v112
	v_permlane32_swap_b32_e32 v111, v113
	s_lshl_b32 s33, s35, 14
	s_add_i32 s36, s33, 0
	s_waitcnt vmcnt(0)
	v_add_u32_e32 v202, s36, v192
	s_cmp_ge_u32 s30, s31
	s_waitcnt vmcnt(3)
	ds_write_b128 v202, v[146:149]
	v_add_u32_e32 v202, s36, v193
	s_cselect_b64 s[8:9], -1, 0
	s_waitcnt vmcnt(2)
	ds_write_b128 v202, v[150:153]
	v_add_u32_e32 v202, s33, v195
	s_and_b64 vcc, exec, s[8:9]
	s_waitcnt vmcnt(1)
	ds_write_b128 v202, v[154:157] offset:49152
	s_waitcnt vmcnt(0)
	ds_write_b128 v202, v[158:161] offset:57344
	s_cbranch_vccnz .LBB0_324
	v_add_co_u32_e32 v146, vcc, 0xfffe0000, v166
	s_nop 1
	v_addc_co_u32_e32 v147, vcc, -1, v167, vcc
	v_add_co_u32_e32 v150, vcc, 0xfb7e0000, v166
	s_nop 1
	v_addc_co_u32_e32 v151, vcc, -1, v167, vcc
	v_add_co_u32_e32 v158, vcc, 0xfb800000, v166
	global_load_dwordx4 v[146:149], v[146:147], off
	s_nop 0
	global_load_dwordx4 v[154:157], v[150:151], off
	v_addc_co_u32_e32 v159, vcc, -1, v167, vcc
	global_load_dwordx4 v[150:153], v[166:167], off
	s_nop 0
	global_load_dwordx4 v[158:161], v[158:159], off
